# attention main loop rewritten by hand: two 4-wave groups ping-pong a matrix phase against a softmax phase, parity-unrolled LDS offsets, SGPR-base staging loads
# speedup vs baseline: 1.0410x; 1.0251x over previous
; __device__ __forceinline__ void unpack8(const u32x4 w, float* f) { f[0] = bf_lo(w.x); f[1] = bf_hi(w.x); f[2] = bf_lo(w.y); f[3] = bf_hi(w.y); f[4] = bf_lo(w.z); f[5] = bf_hi(w.z); f[6] = bf_lo(w.w); f[7] = bf_hi(w.w); }
; __device__ __forceinline__ void attn_unit(const bf16_t* __restrict__ Qb, const bf16_t* __restrict__ KV, const bf16_t* __restrict__ KP, bf16_t* __restrict__ Ob, ...
;   int tid_ = threadIdx.x; asm volatile("" : "+v"(tid_));
;   const int tid = tid_, wid = tid >> 6, lane = tid & 63, r32 = lane & 31, hi = lane >> 5;
;   char* V_lds = lds + OFF_V; char* KN_lds = lds + OFF_KN; char* KP_lds = lds + OFF_KP;
;   float* ws = (float*)(lds + OFF_WS) + wid * 64; float* li_l = ws; float* al_l = ws + 32;
;   float m_reg = -1e30f, l_reg = 0; f32x16 o[4] = {}; bf16x8 qr[12];
;   const bf16_t* Qw = Qb + (size_t)(qrow0 + wid * QBLK + r32) * LDQ + h * QKD + hi * 8;
; #pragma unroll
;   for (int d0 = 0; d0 < 12; ++d0) qr[d0] = ld8(Qw + d0 * 16);
;   {
;     float qf[12][8]; float ss = 0.f;
; #pragma unroll
;     for (int d0 = 0; d0 < 12; ++d0) { const u32x4 w = *reinterpret_cast<const u32x4*>(&qr[d0]); unpack8(w, qf[d0]);
; #pragma unroll
;       for (int jj = 0; jj < 8; ++jj) ss += qf[d0][jj] * qf[d0][jj]; }
;     { auto rr = __builtin_amdgcn_permlane32_swap(__float_as_uint(ss), __float_as_uint(ss), false, false); ss = __uint_as_float(rr[0]) + __uint_as_float(rr[1]); }
;     const float rinv = 1.0f / sqrtf(ss * (1.f / QKD) + EPS);
.LBB0_1452:
	s_ashr_i32 s8, s2, 7
	s_lshl_b32 s6, s2, 8
	v_mov_b32_e32 v162, v188
	s_lshl_b32 s24, s8, 12
	s_and_b32 s6, s6, 0xf00
	s_or_b32 s6, s24, s6
	v_ashrrev_i32_e32 v0, 1, v162
	v_and_b32_e32 v0, 0xffffffe0, v0
	v_and_b32_e32 v184, 31, v162
	v_add_u32_e32 v178, s6, v0
	s_bfe_u32 s3, s2, 0x30004
	v_or_b32_e32 v36, v178, v184
	v_mov_b64_e32 v[0:1], s[14:15]
	v_bfe_u32 v185, v162, 5, 1
	v_mad_i64_i32 v[0:1], s[6:7], v36, s89, v[0:1]
	s_mul_i32 s68, s3, 0x180
	v_lshl_add_u64 v[0:1], v[0:1], 0, s[68:69]
	v_lshlrev_b32_e32 v172, 4, v185
	v_lshl_add_u64 v[32:33], v[0:1], 0, v[172:173]
	global_load_dwordx4 v[20:23], v[32:33], off
	global_load_dwordx4 v[24:27], v[32:33], off offset:32
	global_load_dwordx4 v[16:19], v[32:33], off offset:64
	global_load_dwordx4 v[12:15], v[32:33], off offset:96
	global_load_dwordx4 v[8:11], v[32:33], off offset:128
	global_load_dwordx4 v[4:7], v[32:33], off offset:160
	global_load_dwordx4 v[0:3], v[32:33], off offset:192
	v_and_b32_e32 v124, 32, v162
	global_load_dwordx4 v[112:115], v124, s[20:21] offset:704
	global_load_dwordx4 v[138:141], v124, s[20:21] offset:720
	global_load_dwordx4 v[28:31], v[32:33], off offset:224
	global_load_dwordx4 v[100:103], v[32:33], off offset:256
	global_load_dwordx4 v[96:99], v[32:33], off offset:288
	global_load_dwordx4 v[116:119], v[32:33], off offset:320
	global_load_dwordx4 v[120:123], v[32:33], off offset:352
	v_mov_b32_e32 v125, v173
	s_mov_b64 s[6:7], 0x1000
	s_lshl_b32 s25, s8, 8
	s_add_i32 s11, 0, 0x14000
	s_add_i32 s31, s25, 0x4000
	s_cmp_lg_u32 0, -1
	s_cselect_b32 s34, 0, 0
	s_mov_b32 s50, s48
	s_mov_b32 s51, s48
	s_mov_b32 s52, s48
	s_mov_b32 s53, s48
	s_mov_b32 s54, s48
	s_mov_b32 s55, s48
	s_mov_b32 s56, s48
	s_mov_b32 s57, s48
	s_mov_b32 s58, s48
	s_mov_b32 s59, s48
	s_mov_b32 s60, s48
	s_mov_b32 s61, s48
	s_mov_b32 s62, s48
	s_mov_b32 s63, s48
	v_mov_b64_e32 v[190:191], 0x100
	v_mov_b64_e32 v[252:253], 0xff
	s_waitcnt vmcnt(0)
	v_lshlrev_b32_e32 v229, 16, v20
	v_and_b32_e32 v230, 0xffff0000, v20
	v_lshlrev_b32_e32 v214, 16, v16
	v_and_b32_e32 v213, 0xffff0000, v16
	v_lshlrev_b32_e32 v212, 16, v17
	v_and_b32_e32 v211, 0xffff0000, v17
	v_lshlrev_b32_e32 v210, 16, v18
	v_and_b32_e32 v209, 0xffff0000, v18
	v_lshlrev_b32_e32 v208, 16, v19
	v_and_b32_e32 v207, 0xffff0000, v19
	global_load_dwordx4 v[16:19], v124, s[20:21] offset:656
	v_lshlrev_b32_e32 v227, 16, v21
	v_and_b32_e32 v228, 0xffff0000, v21
	v_lshlrev_b32_e32 v225, 16, v22
	v_and_b32_e32 v226, 0xffff0000, v22
	v_lshlrev_b32_e32 v223, 16, v23
	v_and_b32_e32 v224, 0xffff0000, v23
	global_load_dwordx4 v[20:23], v124, s[20:21] offset:640
	v_mul_f32_e32 v194, v230, v230
	v_fmac_f32_e32 v194, v229, v229
	v_fmac_f32_e32 v194, v227, v227
	v_fmac_f32_e32 v194, v228, v228
	v_fmac_f32_e32 v194, v225, v225
	v_fmac_f32_e32 v194, v226, v226
	v_fmac_f32_e32 v194, v223, v223
	v_lshlrev_b32_e32 v221, 16, v24
	v_fmac_f32_e32 v194, v224, v224
	v_and_b32_e32 v222, 0xffff0000, v24
	v_fmac_f32_e32 v194, v221, v221
	v_lshlrev_b32_e32 v219, 16, v25
	v_fmac_f32_e32 v194, v222, v222
	v_and_b32_e32 v220, 0xffff0000, v25
	v_fmac_f32_e32 v194, v219, v219
	v_lshlrev_b32_e32 v218, 16, v26
	v_fmac_f32_e32 v194, v220, v220
	v_and_b32_e32 v217, 0xffff0000, v26
	v_fmac_f32_e32 v194, v218, v218
	v_lshlrev_b32_e32 v216, 16, v27
	v_fmac_f32_e32 v194, v217, v217
	v_and_b32_e32 v215, 0xffff0000, v27
	v_fmac_f32_e32 v194, v216, v216
	v_fmac_f32_e32 v194, v215, v215
	v_fmac_f32_e32 v194, v214, v214
	v_fmac_f32_e32 v194, v213, v213
	v_fmac_f32_e32 v194, v212, v212
	v_fmac_f32_e32 v194, v211, v211
	v_fmac_f32_e32 v194, v210, v210
	v_lshlrev_b32_e32 v165, 16, v0
	v_and_b32_e32 v164, 0xffff0000, v0
	v_fmac_f32_e32 v194, v209, v209
	v_lshlrev_b32_e32 v0, 6, v36
	v_lshlrev_b32_e32 v163, 16, v1
	v_fmac_f32_e32 v194, v208, v208
	v_and_b32_e32 v239, 0xffff0000, v1
	v_lshl_add_u64 v[24:25], s[18:19], 0, v[124:125]
	v_and_b32_e32 v0, 0xfc0, v0
	v_mov_b32_e32 v1, v173
	v_lshlrev_b32_e32 v206, 16, v12
	v_lshlrev_b32_e32 v180, 16, v4
	v_and_b32_e32 v179, 0xffff0000, v4
	v_lshlrev_b32_e32 v171, 16, v5
	v_and_b32_e32 v170, 0xffff0000, v5
	v_fmac_f32_e32 v194, v207, v207
	v_lshl_add_u64 v[4:5], v[24:25], 0, v[0:1]
	v_and_b32_e32 v205, 0xffff0000, v12
	v_lshlrev_b32_e32 v198, 16, v8
	v_and_b32_e32 v197, 0xffff0000, v8
	v_lshlrev_b32_e32 v196, 16, v9
	v_and_b32_e32 v187, 0xffff0000, v9
	v_lshlrev_b32_e32 v186, 16, v10
	v_and_b32_e32 v183, 0xffff0000, v10
	v_lshlrev_b32_e32 v182, 16, v11
	v_and_b32_e32 v181, 0xffff0000, v11
	v_lshlrev_b32_e32 v169, 16, v6
	v_and_b32_e32 v168, 0xffff0000, v6
	v_lshlrev_b32_e32 v167, 16, v7
	v_and_b32_e32 v166, 0xffff0000, v7
	v_fmac_f32_e32 v194, v206, v206
	v_lshlrev_b32_e32 v237, 16, v2
	v_and_b32_e32 v235, 0xffff0000, v2
	v_lshlrev_b32_e32 v233, 16, v3
	v_and_b32_e32 v231, 0xffff0000, v3
	global_load_dwordx4 v[104:107], v124, s[20:21] offset:16
	global_load_dwordx4 v[108:111], v124, s[20:21]
	global_load_dwordx4 v[88:91], v124, s[20:21] offset:80
	global_load_dwordx4 v[92:95], v124, s[20:21] offset:64
	global_load_dwordx4 v[80:83], v124, s[20:21] offset:144
	global_load_dwordx4 v[84:87], v124, s[20:21] offset:128
	global_load_dwordx4 v[72:75], v124, s[20:21] offset:208
	global_load_dwordx4 v[76:79], v124, s[20:21] offset:192
	global_load_dwordx4 v[64:67], v124, s[20:21] offset:272
	global_load_dwordx4 v[68:71], v124, s[20:21] offset:256
	global_load_dwordx4 v[48:51], v124, s[20:21] offset:336
	global_load_dwordx4 v[56:59], v124, s[20:21] offset:320
	global_load_dwordx4 v[32:35], v124, s[20:21] offset:400
	global_load_dwordx4 v[40:43], v124, s[20:21] offset:384
	global_load_dwordx4 v[8:11], v[4:5], off
	global_load_dwordx4 v[0:3], v[4:5], off offset:16
; __device__ __forceinline__ void unpack8(const u32x4 w, float* f) { f[0] = bf_lo(w.x); f[1] = bf_hi(w.x); f[2] = bf_lo(w.y); f[3] = bf_hi(w.y); f[4] = bf_lo(w.z); f[5] = bf_hi(w.z); f[6] = bf_lo(w.w); f[7] = bf_hi(w.w); }
; __device__ __forceinline__ void attn_unit(const bf16_t* __restrict__ Qb, const bf16_t* __restrict__ KV, const bf16_t* __restrict__ KP, bf16_t* __restrict__ Ob, ...
;     ...
;     float qf[12][8]; float ss = 0.f;
; #pragma unroll
;     for (int d0 = 0; d0 < 12; ++d0) { const u32x4 w = *reinterpret_cast<const u32x4*>(&qr[d0]); unpack8(w, qf[d0]);
; #pragma unroll
;       for (int jj = 0; jj < 8; ++jj) ss += qf[d0][jj] * qf[d0][jj]; }
;     { auto rr = __builtin_amdgcn_permlane32_swap(__float_as_uint(ss), __float_as_uint(ss), false, false); ss = __uint_as_float(rr[0]) + __uint_as_float(rr[1]); }
;     const float rinv = 1.0f / sqrtf(ss * (1.f / QKD) + EPS);
; #pragma unroll
;     for (int d0 = 0; d0 < 12; ++d0) { const f32x4 g0 = *(const f32x4*)(qn + d0 * 16 + hi * 8), g1 = *(const f32x4*)(qn + d0 * 16 + hi * 8 + 4);
; #pragma unroll
;       for (int jj = 0; jj < 8; ++jj) qf[d0][jj] *= rinv * (jj < 4 ? g0[jj & 3] : g1[jj & 3]); }
;     if (do_rope) { const int s = (qrow0 + wid * QBLK + r32) & (SEQ - 1), pr_ = s >> 6, pc_ = s & 63;
; #pragma unroll
;       for (int ax = 0; ax < 2; ++ax) { const float* cp = rope + (ax ? pc_ : pr_) * 16 + hi * 8; const f32x4 c0 = *(const f32x4*)cp, c1 = *(const f32x4*)(cp + 4), s0 = *(const f32x4*)(cp + 1024), s1 = *(const f32x4*)(cp + 1028);
; #pragma unroll
;         for (int jj = 0; jj < 8; ++jj) { const float c = jj < 4 ? c0[jj & 3] : c1[jj & 3], sn = jj < 4 ? s0[jj & 3] : s1[jj & 3], a = qf[8 + 2 * ax][jj], b = qf[9 + 2 * ax][jj];
	v_lshl_add_u64 v[6:7], v[4:5], 0, s[6:7]
	v_add_co_u32_e32 v4, vcc, s49, v4
	v_lshlrev_b32_e32 v204, 16, v13
	v_fmac_f32_e32 v194, v205, v205
	v_addc_co_u32_e32 v5, vcc, 0, v5, vcc
	v_and_b32_e32 v203, 0xffff0000, v13
	v_lshlrev_b32_e32 v202, 16, v14
	v_and_b32_e32 v201, 0xffff0000, v14
	v_lshlrev_b32_e32 v200, 16, v15
	v_and_b32_e32 v199, 0xffff0000, v15
	v_fmac_f32_e32 v194, v204, v204
	v_lshlrev_b32_e32 v241, 16, v28
	v_and_b32_e32 v244, 0xffff0000, v28
	v_lshlrev_b32_e32 v245, 16, v29
	v_and_b32_e32 v240, 0xffff0000, v29
	v_lshlrev_b32_e32 v238, 16, v30
	v_and_b32_e32 v236, 0xffff0000, v30
	v_lshlrev_b32_e32 v234, 16, v31
	v_and_b32_e32 v232, 0xffff0000, v31
	global_load_dwordx4 v[12:15], v[4:5], off
	s_nop 0
	global_load_dwordx4 v[4:7], v[6:7], off offset:16
	s_nop 0
	global_load_dwordx4 v[52:55], v124, s[20:21] offset:464
	global_load_dwordx4 v[60:63], v124, s[20:21] offset:448
	global_load_dwordx4 v[36:39], v124, s[20:21] offset:512
	global_load_dwordx4 v[28:31], v124, s[20:21] offset:528
	global_load_dwordx4 v[44:47], v124, s[20:21] offset:576
	s_nop 0
	global_load_dwordx4 v[124:127], v124, s[20:21] offset:592
	v_fmac_f32_e32 v194, v203, v203
	v_fmac_f32_e32 v194, v202, v202
	v_fmac_f32_e32 v194, v201, v201
	v_fmac_f32_e32 v194, v200, v200
	v_fmac_f32_e32 v194, v199, v199
	v_fmac_f32_e32 v194, v198, v198
	v_fmac_f32_e32 v194, v197, v197
	v_fmac_f32_e32 v194, v196, v196
	v_fmac_f32_e32 v194, v187, v187
	v_fmac_f32_e32 v194, v186, v186
	v_fmac_f32_e32 v194, v183, v183
	v_fmac_f32_e32 v194, v182, v182
	v_fmac_f32_e32 v194, v181, v181
	v_fmac_f32_e32 v194, v180, v180
	v_fmac_f32_e32 v194, v179, v179
	v_fmac_f32_e32 v194, v171, v171
	v_fmac_f32_e32 v194, v170, v170
	v_fmac_f32_e32 v194, v169, v169
	v_fmac_f32_e32 v194, v168, v168
	v_fmac_f32_e32 v194, v167, v167
	v_fmac_f32_e32 v194, v166, v166
	v_fmac_f32_e32 v194, v165, v165
	v_fmac_f32_e32 v194, v164, v164
	v_fmac_f32_e32 v194, v163, v163
	v_fmac_f32_e32 v194, v239, v239
	v_fmac_f32_e32 v194, v237, v237
	v_fmac_f32_e32 v194, v235, v235
	v_fmac_f32_e32 v194, v233, v233
	v_fmac_f32_e32 v194, v231, v231
	v_fmac_f32_e32 v194, v241, v241
	v_fmac_f32_e32 v194, v244, v244
	v_fmac_f32_e32 v194, v245, v245
	v_fmac_f32_e32 v194, v240, v240
	v_fmac_f32_e32 v194, v238, v238
	v_fmac_f32_e32 v194, v236, v236
	v_fmac_f32_e32 v194, v234, v234
	v_lshlrev_b32_e32 v159, 16, v100
	v_lshlrev_b32_e32 v158, 16, v96
	v_fmac_f32_e32 v194, v232, v232
	v_lshlrev_b32_e32 v154, 16, v97
	v_and_b32_e32 v156, 0xffff0000, v97
	v_and_b32_e32 v161, 0xffff0000, v100
	v_and_b32_e32 v160, 0xffff0000, v96
	v_pk_mul_f32 v[96:97], v[158:159], v[158:159]
	v_lshlrev_b32_e32 v146, 16, v99
	v_and_b32_e32 v148, 0xffff0000, v99
	v_lshlrev_b32_e32 v150, 16, v98
	v_and_b32_e32 v152, 0xffff0000, v98
	v_lshlrev_b32_e32 v155, 16, v101
	v_add_f32_e32 v97, v97, v194
	v_pk_mul_f32 v[98:99], v[160:161], v[160:161]
	v_pk_mul_f32 v[192:193], v[154:155], v[154:155]
	v_and_b32_e32 v157, 0xffff0000, v101
	v_add_f32_e32 v97, v99, v97
	v_lshlrev_b32_e32 v151, 16, v102
	v_pk_mul_f32 v[100:101], v[156:157], v[156:157]
	v_add_f32_e32 v97, v193, v97
	v_lshlrev_b32_e32 v128, 16, v123
	v_lshlrev_b32_e32 v129, 16, v119
	v_mov_b32_e32 v130, v140
	s_waitcnt vmcnt(25)
	v_mov_b32_e32 v131, v18
	v_and_b32_e32 v133, 0xffff0000, v119
	v_and_b32_e32 v132, 0xffff0000, v123
	v_mov_b32_e32 v18, v141
	v_lshlrev_b32_e32 v135, 16, v118
	v_lshlrev_b32_e32 v134, 16, v122
	v_and_b32_e32 v119, 0xffff0000, v118
	v_and_b32_e32 v118, 0xffff0000, v122
	v_lshlrev_b32_e32 v123, 16, v117
	v_lshlrev_b32_e32 v122, 16, v121
	v_and_b32_e32 v141, 0xffff0000, v117
	v_and_b32_e32 v140, 0xffff0000, v121
	v_lshlrev_b32_e32 v143, 16, v116
	v_lshlrev_b32_e32 v142, 16, v120
	v_and_b32_e32 v117, 0xffff0000, v116
	v_and_b32_e32 v116, 0xffff0000, v120
	v_pk_mul_f32 v[120:121], v[150:151], v[150:151]
	v_and_b32_e32 v153, 0xffff0000, v102
	v_add_f32_e32 v97, v101, v97
	v_lshlrev_b32_e32 v147, 16, v103
	v_and_b32_e32 v149, 0xffff0000, v103
	v_pk_mul_f32 v[102:103], v[152:153], v[152:153]
	v_add_f32_e32 v97, v121, v97
	v_mov_b32_e32 v144, v112
	s_waitcnt vmcnt(24)
	v_mov_b32_e32 v145, v20
	v_mov_b32_e32 v20, v113
	v_pk_mul_f32 v[112:113], v[146:147], v[146:147]
	v_add_f32_e32 v97, v103, v97
	v_mov_b32_e32 v136, v138
	v_mov_b32_e32 v137, v16
	v_mov_b32_e32 v16, v139
	v_mov_b32_e32 v138, v114
	v_mov_b32_e32 v139, v22
	v_mov_b32_e32 v22, v115
	v_pk_mul_f32 v[114:115], v[148:149], v[148:149]
	v_add_f32_e32 v97, v113, v97
	v_add_f32_e32 v97, v115, v97
	v_add_f32_e32 v96, v96, v97
	v_add_f32_e32 v101, v98, v96
	v_add_f32_e32 v101, v192, v101
	v_add_f32_e32 v100, v100, v101
	v_add_f32_e32 v100, v120, v100
	v_add_f32_e32 v100, v102, v100
	v_add_f32_e32 v102, v112, v100
	v_pk_mul_f32 v[100:101], v[142:143], v[142:143]
	v_add_f32_e32 v102, v114, v102
	v_and_b32_e32 v26, 0xfc0, v178
	v_mov_b32_e32 v27, v173
	v_pk_mul_f32 v[112:113], v[116:117], v[116:117]
	v_add_f32_e32 v101, v101, v102
	v_lshl_add_u64 v[174:175], v[24:25], 0, v[26:27]
	v_pk_mul_f32 v[120:121], v[122:123], v[122:123]
	v_add_f32_e32 v101, v113, v101
	v_lshl_add_u64 v[176:177], v[174:175], 0, s[6:7]
	v_pk_mul_f32 v[242:243], v[140:141], v[140:141]
	v_add_f32_e32 v101, v121, v101
	global_load_dwordx4 v[96:99], v[176:177], off offset:16
	v_pk_mul_f32 v[176:177], v[134:135], v[134:135]
	v_add_f32_e32 v101, v243, v101
	v_pk_mul_f32 v[192:193], v[118:119], v[118:119]
	v_add_f32_e32 v101, v177, v101
	v_add_f32_e32 v101, v193, v101
	v_fmac_f32_e32 v101, v129, v129
	v_fmac_f32_e32 v101, v133, v133
	v_add_f32_e32 v113, v100, v101
	v_add_f32_e32 v121, v112, v113
	global_load_dwordx4 v[24:27], v[174:175], off offset:16
	global_load_dwordx4 v[100:103], v[174:175], off
	v_add_co_u32_e32 v194, vcc, s49, v174
	v_add_f32_e32 v174, v120, v121
	s_nop 0
	v_addc_co_u32_e32 v195, vcc, 0, v175, vcc
	v_add_f32_e32 v177, v242, v174
	global_load_dwordx4 v[112:115], v[194:195], off
	v_mov_b32_e32 v174, v132
	v_mov_b32_e32 v175, v128
	v_add_f32_e32 v176, v176, v177
	v_pk_mul_f32 v[174:175], v[174:175], v[174:175]
	v_add_f32_e32 v176, v192, v176
	v_add_f32_e32 v175, v175, v176
	v_add_f32_e32 v174, v174, v175
	v_mov_b32_e32 v175, v174
	s_nop 1
	v_permlane32_swap_b32_e32 v174, v175
	v_add_f32_e32 v174, v174, v175
	v_fmamk_f32 v174, v174, 0x3baaaaab, v189
	v_mul_f32_e32 v175, 0x4f800000, v174
	v_cmp_gt_f32_e32 vcc, s91, v174
	s_waitcnt vmcnt(12)
; __device__ __forceinline__ void attn_unit(const bf16_t* __restrict__ Qb, const bf16_t* __restrict__ KV, const bf16_t* __restrict__ KP, bf16_t* __restrict__ Ob, ...
;     ...
;     const float rinv = 1.0f / sqrtf(ss * (1.f / QKD) + EPS);
; #pragma unroll
;     for (int d0 = 0; d0 < 12; ++d0) { const f32x4 g0 = *(const f32x4*)(qn + d0 * 16 + hi * 8), g1 = *(const f32x4*)(qn + d0 * 16 + hi * 8 + 4);
; #pragma unroll
;       for (int jj = 0; jj < 8; ++jj) qf[d0][jj] *= rinv * (jj < 4 ? g0[jj & 3] : g1[jj & 3]); }
	v_mov_b32_e32 v120, v2
	s_waitcnt vmcnt(10)
	v_mov_b32_e32 v121, v6
	v_cndmask_b32_e32 v176, v174, v175, vcc
	v_sqrt_f32_e32 v177, v176
	s_waitcnt vmcnt(4)
	v_mov_b32_e32 v174, v126
	v_mov_b32_e32 v175, v30
	v_mov_b32_e32 v30, v127
	v_add_u32_e32 v126, -1, v177
	v_fma_f32 v127, -v126, v177, v176
	v_cmp_ge_f32_e64 s[6:7], 0, v127
	v_add_u32_e32 v127, 1, v177
	s_mov_b32 s49, s48
	v_cndmask_b32_e64 v126, v177, v126, s[6:7]
	v_fma_f32 v177, -v127, v177, v176
	v_cmp_lt_f32_e64 s[6:7], 0, v177
	s_nop 1
	v_cndmask_b32_e64 v126, v126, v127, s[6:7]
	v_mul_f32_e32 v127, 0x37800000, v126
	v_cndmask_b32_e32 v126, v126, v127, vcc
	v_cmp_class_f32_e32 vcc, v176, v254
	v_mov_b32_e32 v127, v28
	v_mov_b32_e32 v28, v125
	v_cndmask_b32_e32 v176, v126, v176, vcc
	v_div_scale_f32 v177, s[6:7], v176, v176, 1.0
	v_rcp_f32_e32 v192, v177
	v_mov_b32_e32 v126, v124
	v_mov_b32_e32 v124, v0
	v_mov_b32_e32 v125, v4
	v_fma_f32 v193, -v177, v192, 1.0
	v_fmac_f32_e32 v192, v193, v192
	v_div_scale_f32 v193, vcc, 1.0, v176, 1.0
	v_mul_f32_e32 v194, v193, v192
	v_fma_f32 v195, -v177, v194, v193
	v_fmac_f32_e32 v194, v195, v192
	v_fma_f32 v177, -v177, v194, v193
	v_div_fmas_f32 v177, v177, v192, v194
	v_div_fixup_f32 v176, v177, v176, 1.0
	v_mul_f32_e32 v109, v109, v176
	v_mul_f32_e32 v230, v109, v230
	v_mov_b32_e32 v109, v38
	v_mov_b32_e32 v38, v47
	v_mov_b32_e32 v47, v36
	v_mul_f32_e32 v36, v88, v176
	v_mul_f32_e32 v218, v36, v218
	v_mul_f32_e32 v36, v89, v176
	v_mul_f32_e32 v217, v36, v217
	v_mul_f32_e32 v36, v90, v176
	v_mul_f32_e32 v90, v36, v216
	v_mul_f32_e32 v36, v91, v176
	v_mul_f32_e32 v91, v36, v215
	v_mul_f32_e32 v36, v84, v176
	v_mul_f32_e32 v84, v36, v214
	v_mul_f32_e32 v36, v85, v176
	v_mul_f32_e32 v85, v36, v213
	v_mul_f32_e32 v36, v86, v176
	v_mul_f32_e32 v86, v36, v212
	v_mul_f32_e32 v36, v87, v176
	v_mul_f32_e32 v87, v36, v211
	v_mul_f32_e32 v36, v176, v80
	v_mul_f32_e32 v80, v36, v210
	v_mul_f32_e32 v36, v176, v81
	v_mul_f32_e32 v81, v36, v209
	v_mul_f32_e32 v36, v176, v82
	v_mul_f32_e32 v82, v36, v208
	v_mul_f32_e32 v36, v176, v83
	v_mul_f32_e32 v83, v36, v207
	v_mul_f32_e32 v36, v176, v76
	v_mul_f32_e32 v76, v36, v206
	v_mul_f32_e32 v36, v176, v77
	v_mul_f32_e32 v77, v36, v205
	v_mul_f32_e32 v36, v176, v78
	v_mul_f32_e32 v78, v36, v204
	v_mul_f32_e32 v36, v176, v79
	v_mul_f32_e32 v79, v36, v203
	v_mul_f32_e32 v36, v176, v72
	v_mul_f32_e32 v72, v36, v202
	v_mul_f32_e32 v36, v176, v73
	v_mul_f32_e32 v73, v36, v201
	v_mul_f32_e32 v36, v176, v74
	v_mul_f32_e32 v74, v36, v200
	v_mul_f32_e32 v36, v176, v75
	v_mul_f32_e32 v75, v36, v199
	v_mul_f32_e32 v36, v176, v68
	v_mul_f32_e32 v68, v36, v198
	v_mul_f32_e32 v36, v176, v69
	v_mul_f32_e32 v69, v36, v197
	v_mul_f32_e32 v36, v176, v70
	v_mul_f32_e32 v70, v36, v196
	v_mul_f32_e32 v36, v176, v71
	v_mul_f32_e32 v71, v36, v187
	v_mul_f32_e32 v36, v176, v64
	v_mul_f32_e32 v64, v36, v186
	v_mul_f32_e32 v36, v176, v65
	v_mul_f32_e32 v65, v36, v183
	v_mul_f32_e32 v36, v176, v66
	v_mul_f32_e32 v66, v36, v182
	v_mul_f32_e32 v36, v176, v67
	v_mul_f32_e32 v67, v36, v181
	v_mul_f32_e32 v36, v176, v56
	v_mul_f32_e32 v56, v36, v180
	v_mul_f32_e32 v36, v176, v57
	v_mul_f32_e32 v57, v36, v179
	v_mul_f32_e32 v36, v176, v58
	v_mul_f32_e32 v32, v176, v32
	v_mul_f32_e32 v58, v36, v171
	v_mul_f32_e32 v171, v32, v237
	v_mul_f32_e32 v32, v176, v33
	v_mul_f32_e32 v179, v32, v235
	v_mul_f32_e32 v32, v176, v34
	v_mul_f32_e32 v36, v176, v59
	v_mul_f32_e32 v180, v32, v233
	v_mul_f32_e32 v32, v176, v35
	v_mul_f32_e32 v59, v36, v170
	v_mul_f32_e32 v36, v176, v48
	v_mul_f32_e32 v181, v32, v231
	v_mul_f32_e32 v32, v176, v60
	v_mul_f32_e32 v169, v36, v169
	v_mul_f32_e32 v36, v176, v49
	v_mul_f32_e32 v60, v32, v241
	v_mul_f32_e32 v32, v176, v61
	v_mul_f32_e32 v168, v36, v168
	v_mul_f32_e32 v36, v176, v50
	v_mul_f32_e32 v61, v32, v244
	v_mul_f32_e32 v32, v176, v62
	v_mul_f32_e32 v167, v36, v167
	v_mul_f32_e32 v36, v176, v51
	v_mul_f32_e32 v62, v32, v245
	v_mul_f32_e32 v32, v176, v63
	v_mul_f32_e32 v166, v36, v166
	v_mul_f32_e32 v36, v176, v40
	v_mul_f32_e32 v63, v32, v240
	v_mul_f32_e32 v32, v176, v52
	v_mul_f32_e32 v165, v36, v165
	v_mul_f32_e32 v36, v176, v41
	v_mul_f32_e32 v182, v32, v238
	v_mul_f32_e32 v32, v176, v53
	v_mul_f32_e32 v108, v108, v176
	v_mul_f32_e32 v177, v104, v176
	v_mul_f32_e32 v164, v36, v164
	v_mul_f32_e32 v36, v176, v42
	v_mul_f32_e32 v183, v32, v236
	v_mul_f32_e32 v32, v176, v54
	v_mul_f32_e32 v229, v108, v229
	v_mul_f32_e32 v177, v177, v225
	v_mov_b32_e32 v108, v46
	v_mov_b32_e32 v46, v44
	v_mul_f32_e32 v163, v36, v163
	v_mul_f32_e32 v36, v176, v43
	v_mul_f32_e32 v54, v32, v234
	v_mul_f32_e32 v32, v176, v55
	v_mul_f32_e32 v170, v36, v239
	v_mul_f32_e32 v55, v32, v232
	v_pk_mul_f32 v[32:33], v[176:177], v[46:47] op_sel_hi:[0,1]
	v_mov_b32_e32 v36, v45
	s_waitcnt vmcnt(1)
	v_mov_b32_e32 v88, v100
	s_waitcnt vmcnt(0)
; __device__ __forceinline__ u32x4 pack8(const float* f) { u32x4 w; w.x = cvt_pk_bf16(f[0], f[1]); w.y = cvt_pk_bf16(f[2], f[3]); w.z = cvt_pk_bf16(f[4], f[5]); w.w = cvt_pk_bf16(f[6], f[7]); return w; }
; __device__ __forceinline__ void attn_unit(const bf16_t* __restrict__ Qb, const bf16_t* __restrict__ KV, const bf16_t* __restrict__ KP, bf16_t* __restrict__ Ob, ...
;     ...
;     if (do_rope) { const int s = (qrow0 + wid * QBLK + r32) & (SEQ - 1), pr_ = s >> 6, pc_ = s & 63;
; #pragma unroll
;       for (int ax = 0; ax < 2; ++ax) { const float* cp = rope + (ax ? pc_ : pr_) * 16 + hi * 8; const f32x4 c0 = *(const f32x4*)cp, c1 = *(const f32x4*)(cp + 4), s0 = *(const f32x4*)(cp + 1024), s1 = *(const f32x4*)(cp + 1028);
; #pragma unroll
;         for (int jj = 0; jj < 8; ++jj) { const float c = jj < 4 ? c0[jj & 3] : c1[jj & 3], sn = jj < 4 ? s0[jj & 3] : s1[jj & 3], a = qf[8 + 2 * ax][jj], b = qf[9 + 2 * ax][jj];
;           qf[8 + 2 * ax][jj] = a * c - b * sn; qf[9 + 2 * ax][jj] = b * c + a * sn; } } }
; #pragma unroll
;     for (int d0 = 0; d0 < 12; ++d0) { const u32x4 w = pack8(qf[d0]); qr[d0] = *reinterpret_cast<const bf16x8*>(&w); }
	v_mov_b32_e32 v89, v112
	v_pk_mul_f32 v[32:33], v[32:33], v[158:159]
	v_pk_mul_f32 v[34:35], v[176:177], v[36:37] op_sel_hi:[0,1]
	v_mov_b32_e32 v52, v112
	v_mov_b32_e32 v53, v100
	v_pk_mul_f32 v[34:35], v[34:35], v[160:161]
	v_pk_mul_f32 v[52:53], v[32:33], v[52:53]
	v_pk_mul_f32 v[32:33], v[32:33], v[88:89]
	v_mov_b32_e32 v100, v113
	v_sub_f32_e32 v52, v53, v52
	v_add_f32_e32 v53, v32, v33
	v_pk_mul_f32 v[32:33], v[34:35], v[100:101]
	v_mov_b32_e32 v112, v101
	v_pk_mul_f32 v[36:37], v[176:177], v[108:109] op_sel_hi:[0,1]
	v_sub_f32_e32 v88, v33, v32
	v_pk_mul_f32 v[32:33], v[34:35], v[112:113]
	v_mul_f32_e32 v110, v110, v176
	v_mul_f32_e32 v111, v111, v176
	v_pk_mul_f32 v[36:37], v[36:37], v[154:155]
	v_add_f32_e32 v34, v32, v33
	v_mov_b32_e32 v32, v114
	v_mov_b32_e32 v33, v102
	v_mul_f32_e32 v227, v110, v227
	v_mul_f32_e32 v228, v111, v228
	v_mov_b32_e32 v110, v102
	v_mov_b32_e32 v111, v114
	v_pk_mul_f32 v[38:39], v[176:177], v[38:39] op_sel_hi:[0,1]
	v_pk_mul_f32 v[32:33], v[36:37], v[32:33]
	v_pk_mul_f32 v[38:39], v[38:39], v[156:157]
	v_sub_f32_e32 v35, v33, v32
	v_pk_mul_f32 v[32:33], v[36:37], v[110:111]
	v_mov_b32_e32 v102, v115
	v_add_f32_e32 v36, v32, v33
	v_pk_mul_f32 v[32:33], v[38:39], v[102:103]
	v_mov_b32_e32 v114, v103
	v_pk_mul_f32 v[40:41], v[176:177], v[126:127] op_sel_hi:[0,1]
	v_sub_f32_e32 v37, v33, v32
	v_pk_mul_f32 v[32:33], v[38:39], v[114:115]
	v_pk_mul_f32 v[40:41], v[40:41], v[150:151]
	v_add_f32_e32 v38, v32, v33
	v_mov_b32_e32 v32, v96
	v_mov_b32_e32 v33, v24
	v_mul_f32_e32 v193, v106, v176
	v_mul_f32_e32 v194, v107, v176
	v_mov_b32_e32 v106, v24
	v_mov_b32_e32 v107, v96
	v_pk_mul_f32 v[28:29], v[176:177], v[28:29] op_sel_hi:[0,1]
	v_pk_mul_f32 v[32:33], v[40:41], v[32:33]
	v_pk_mul_f32 v[28:29], v[28:29], v[152:153]
	v_sub_f32_e32 v39, v33, v32
	v_pk_mul_f32 v[32:33], v[40:41], v[106:107]
	v_mov_b32_e32 v24, v97
	v_mov_b32_e32 v96, v25
	v_pk_mul_f32 v[42:43], v[176:177], v[174:175] op_sel_hi:[0,1]
	v_add_f32_e32 v40, v32, v33
	v_pk_mul_f32 v[32:33], v[28:29], v[24:25]
	v_pk_mul_f32 v[24:25], v[28:29], v[96:97]
	v_pk_mul_f32 v[42:43], v[42:43], v[146:147]
	v_add_f32_e32 v28, v24, v25
	v_mov_b32_e32 v24, v98
	v_mov_b32_e32 v25, v26
	v_mul_f32_e32 v192, v105, v176
	v_mov_b32_e32 v104, v26
	v_mov_b32_e32 v105, v98
	v_pk_mul_f32 v[30:31], v[176:177], v[30:31] op_sel_hi:[0,1]
	v_pk_mul_f32 v[24:25], v[42:43], v[24:25]
	v_pk_mul_f32 v[30:31], v[30:31], v[148:149]
	v_sub_f32_e32 v29, v25, v24
	v_pk_mul_f32 v[24:25], v[42:43], v[104:105]
	v_mov_b32_e32 v26, v99
	v_sub_f32_e32 v32, v33, v32
	v_add_f32_e32 v33, v24, v25
	v_pk_mul_f32 v[24:25], v[30:31], v[26:27]
	v_mov_b32_e32 v98, v27
	v_pk_mul_f32 v[44:45], v[176:177], v[144:145] op_sel_hi:[0,1]
	v_sub_f32_e32 v26, v25, v24
	v_pk_mul_f32 v[24:25], v[30:31], v[98:99]
	v_pk_mul_f32 v[44:45], v[44:45], v[142:143]
	v_add_f32_e32 v27, v24, v25
	v_mov_b32_e32 v24, v12
	v_mov_b32_e32 v25, v8
	v_mul_f32_e32 v243, v94, v176
	v_mul_f32_e32 v246, v95, v176
	v_mov_b32_e32 v94, v8
	v_mov_b32_e32 v95, v12
	v_pk_mul_f32 v[20:21], v[176:177], v[20:21] op_sel_hi:[0,1]
	v_pk_mul_f32 v[24:25], v[44:45], v[24:25]
	v_pk_mul_f32 v[20:21], v[20:21], v[116:117]
	v_sub_f32_e32 v30, v25, v24
	v_pk_mul_f32 v[24:25], v[44:45], v[94:95]
	v_mov_b32_e32 v8, v13
	v_mov_b32_e32 v12, v9
	v_pk_mul_f32 v[46:47], v[176:177], v[138:139] op_sel_hi:[0,1]
	v_add_f32_e32 v31, v24, v25
	v_pk_mul_f32 v[24:25], v[20:21], v[8:9]
	v_pk_mul_f32 v[8:9], v[20:21], v[12:13]
	v_pk_mul_f32 v[46:47], v[46:47], v[122:123]
	v_add_f32_e32 v12, v8, v9
	v_mov_b32_e32 v8, v14
	v_mov_b32_e32 v9, v10
	v_mul_f32_e32 v195, v92, v176
	v_mul_f32_e32 v242, v93, v176
	v_mov_b32_e32 v92, v10
	v_mov_b32_e32 v93, v14
	v_pk_mul_f32 v[22:23], v[176:177], v[22:23] op_sel_hi:[0,1]
	v_pk_mul_f32 v[8:9], v[46:47], v[8:9]
	v_pk_mul_f32 v[22:23], v[22:23], v[140:141]
	v_sub_f32_e32 v13, v9, v8
	v_pk_mul_f32 v[8:9], v[46:47], v[92:93]
	v_mov_b32_e32 v10, v15
	v_add_f32_e32 v20, v8, v9
	v_pk_mul_f32 v[8:9], v[22:23], v[10:11]
	v_mov_b32_e32 v14, v11
	v_pk_mul_f32 v[48:49], v[176:177], v[136:137] op_sel_hi:[0,1]
	v_sub_f32_e32 v10, v9, v8
	v_pk_mul_f32 v[8:9], v[22:23], v[14:15]
	v_pk_mul_f32 v[48:49], v[48:49], v[134:135]
	v_add_f32_e32 v11, v8, v9
	v_mov_b32_e32 v8, v4
	v_mov_b32_e32 v9, v0
	v_pk_mul_f32 v[16:17], v[176:177], v[16:17] op_sel_hi:[0,1]
	v_pk_mul_f32 v[8:9], v[48:49], v[8:9]
	v_pk_mul_f32 v[16:17], v[16:17], v[118:119]
	v_sub_f32_e32 v14, v9, v8
	v_pk_mul_f32 v[8:9], v[48:49], v[124:125]
	v_mov_b32_e32 v0, v5
	v_mov_b32_e32 v4, v1
	v_pk_mul_f32 v[50:51], v[176:177], v[130:131] op_sel_hi:[0,1]
	v_add_f32_e32 v15, v8, v9
	v_pk_mul_f32 v[8:9], v[16:17], v[0:1]
	v_pk_mul_f32 v[0:1], v[16:17], v[4:5]
	v_pk_mul_f32 v[50:51], v[50:51], v[128:129]
	v_add_f32_e32 v4, v0, v1
	v_mov_b32_e32 v0, v6
	v_mov_b32_e32 v1, v2
	v_pk_mul_f32 v[18:19], v[176:177], v[18:19] op_sel_hi:[0,1]
	v_pk_mul_f32 v[0:1], v[50:51], v[0:1]
	v_pk_mul_f32 v[18:19], v[18:19], v[132:133]
	v_sub_f32_e32 v5, v1, v0
	v_pk_mul_f32 v[0:1], v[50:51], v[120:121]
	v_mov_b32_e32 v2, v7
	v_sub_f32_e32 v8, v9, v8
	v_add_f32_e32 v9, v0, v1
	v_pk_mul_f32 v[0:1], v[18:19], v[2:3]
	v_mov_b32_e32 v6, v3
	v_sub_f32_e32 v2, v1, v0
	v_pk_mul_f32 v[0:1], v[18:19], v[6:7]
	v_mul_f32_e32 v192, v192, v226
	v_mul_f32_e32 v193, v193, v223
	v_mul_f32_e32 v194, v194, v224
	v_mul_f32_e32 v195, v195, v221
	v_mul_f32_e32 v221, v242, v222
	v_mul_f32_e32 v219, v243, v219
	v_mul_f32_e32 v220, v246, v220
	v_add_f32_e32 v0, v0, v1
	v_cvt_pk_bf16_f32 v136, v229, v230
	v_cvt_pk_bf16_f32 v137, v227, v228
	v_cvt_pk_bf16_f32 v138, v177, v192
	v_cvt_pk_bf16_f32 v139, v193, v194
	v_cvt_pk_bf16_f32 v132, v195, v221
; __device__ __forceinline__ u32x4 pack8(const float* f) { u32x4 w; w.x = cvt_pk_bf16(f[0], f[1]); w.y = cvt_pk_bf16(f[2], f[3]); w.z = cvt_pk_bf16(f[4], f[5]); w.w = cvt_pk_bf16(f[6], f[7]); return w; }
; __device__ __forceinline__ int v_st(int k, int c) { const int kk = (k & ~0xC) | ((k & 4) << 1) | ((k & 8) >> 1); return ((kk >> 3) * 4 + (c >> 5)) * 512 + ((kk & 7) * 32 + (c & 31)) * 2; }
; __device__ __forceinline__ int v_rd_base(int lane) { return ((lane & 3) << 3) | (((lane >> 2) & 3) << 6) | (((lane >> 4) & 1) << 5) | (((lane >> 5) & 1) << 8); }
; #define SLOAD(j) do { const int r0_ = TROW(j); const bf16_t* a_ = KVh + (size_t)(r0_ + sr) * LDKV + sc; const bf16_t* b_ = KVh + (size_t)(r0_ + 32 + sr) * LDKV + sc; \
;     vs0 = ld8(a_ + 128); vs1 = ld8(b_ + 128); ks0 = ld8(a_); ks1 = ld8(b_); kp0 = ld8(KPh + (size_t)(r0_ + pr) * LDKP + pc); } while (0)
; #define SWRITE(b) do { *(bf16x8*)(V_lds + (b) * SHM_V + vst0) = vs0; *(bf16x8*)(V_lds + (b) * SHM_V + vst1) = vs1; const int kc = sc * 2; \
;     *(bf16x8*)(KN_lds + (b) * SHM_KN + KSWZ(sr, kc)) = ks0; *(bf16x8*)(KN_lds + (b) * SHM_KN + KSWZ(32 + sr, kc)) = ks1; \
;     *(bf16x8*)(KP_lds + (b) * SHM_KP + KPSWZ(pr, pc * 2)) = kp0; } while (0)
; #define SWAIT() asm volatile("s_waitcnt vmcnt(0)" ::: "memory")
; __device__ __forceinline__ void attn_unit(const bf16_t* __restrict__ Qb, const bf16_t* __restrict__ KV, const bf16_t* __restrict__ KP, bf16_t* __restrict__ Ob, ...
;     ...
;     for (int d0 = 0; d0 < 12; ++d0) { const u32x4 w = pack8(qf[d0]); qr[d0] = *reinterpret_cast<const bf16x8*>(&w); }
;   }
;   const int sr = tid >> 4, sc = (tid & 15) * 8, vst0 = v_st(sr, sc), vst1 = v_st(32 + sr, sc);
;   const int pr = tid >> 3, pc = (tid & 7) * 8;
;   const int vb0 = (int)(uintptr_t)V_lds + v_rd_base(lane);
;   bf16x8 vs0, vs1, ks0, ks1, kp0;
;   const bf16_t* KVh = KV + h * 256; const bf16_t* KPh = KP + h * QKR;
;     ...
;   f32x16 pA0, pA1, pB0, pB1; float mnA, mnB, alA, alB; bf16x8 pa0, pa1, pa2, pa3;
;   SLOAD(0); SWAIT(); SWRITE(0); __syncthreads();
;   qkt(pA0, pA1, KN_lds, KP_lds, qr, r32, hi); partialSM(pA0, pA1, m_reg, mnA, alA);
;   SLOAD(1);
;   SWAIT(); SWRITE(1); __syncthreads();
	v_cvt_pk_bf16_f32 v133, v219, v220
	v_cvt_pk_bf16_f32 v134, v218, v217
	v_cvt_pk_bf16_f32 v135, v90, v91
	v_cvt_pk_bf16_f32 v128, v84, v85
	v_cvt_pk_bf16_f32 v129, v86, v87
	v_cvt_pk_bf16_f32 v130, v80, v81
	v_cvt_pk_bf16_f32 v131, v82, v83
	v_cvt_pk_bf16_f32 v124, v76, v77
	v_cvt_pk_bf16_f32 v125, v78, v79
	v_cvt_pk_bf16_f32 v126, v72, v73
	v_cvt_pk_bf16_f32 v127, v74, v75
	v_cvt_pk_bf16_f32 v120, v68, v69
	v_cvt_pk_bf16_f32 v121, v70, v71
	v_cvt_pk_bf16_f32 v122, v64, v65
	v_cvt_pk_bf16_f32 v123, v66, v67
	v_cvt_pk_bf16_f32 v140, v56, v57
	v_cvt_pk_bf16_f32 v141, v58, v59
	v_cvt_pk_bf16_f32 v142, v169, v168
	v_cvt_pk_bf16_f32 v143, v167, v166
	v_cvt_pk_bf16_f32 v116, v165, v164
	v_cvt_pk_bf16_f32 v117, v163, v170
	v_cvt_pk_bf16_f32 v118, v171, v179
	v_cvt_pk_bf16_f32 v119, v180, v181
	v_cvt_pk_bf16_f32 v112, v60, v61
	v_cvt_pk_bf16_f32 v113, v62, v63
	v_cvt_pk_bf16_f32 v114, v182, v183
	v_cvt_pk_bf16_f32 v115, v54, v55
	v_cvt_pk_bf16_f32 v108, v52, v88
	v_lshlrev_b32_e32 v52, 3, v162
	v_sub_f32_e32 v24, v25, v24
	v_cvt_pk_bf16_f32 v109, v35, v37
	v_cvt_pk_bf16_f32 v110, v39, v32
	v_cvt_pk_bf16_f32 v111, v29, v26
	v_cvt_pk_bf16_f32 v104, v53, v34
	v_cvt_pk_bf16_f32 v105, v36, v38
	v_cvt_pk_bf16_f32 v106, v40, v28
	v_cvt_pk_bf16_f32 v107, v33, v27
	v_cvt_pk_bf16_f32 v100, v30, v24
	v_cvt_pk_bf16_f32 v101, v13, v10
	v_cvt_pk_bf16_f32 v102, v14, v8
	v_cvt_pk_bf16_f32 v103, v5, v2
	v_cvt_pk_bf16_f32 v96, v31, v12
	v_cvt_pk_bf16_f32 v97, v20, v11
	v_cvt_pk_bf16_f32 v98, v15, v4
	v_cvt_pk_bf16_f32 v99, v9, v0
	v_ashrrev_i32_e32 v198, 4, v162
	v_and_b32_e32 v0, 0x78, v52
	v_lshlrev_b32_e32 v48, 1, v0
	s_lshl_b32 s6, s3, 9
	v_add_u32_e32 v0, s31, v198
	s_add_u32 s6, s27, s6
	v_ashrrev_i32_e32 v1, 31, v0
	s_addc_u32 s7, s28, 0
	v_lshlrev_b64 v[0:1], 12, v[0:1]
	v_lshl_add_u64 v[0:1], s[6:7], 0, v[0:1]
	v_mov_b32_e32 v49, v173
	v_add_u32_e32 v53, s25, v198
	v_lshl_add_u64 v[8:9], v[0:1], 0, v[48:49]
	v_add_u32_e32 v0, 0x4020, v53
	v_ashrrev_i32_e32 v1, 31, v0
	v_lshlrev_b64 v[0:1], 12, v[0:1]
	v_lshl_add_u64 v[4:5], s[6:7], 0, v[0:1]
	global_load_dwordx4 v[0:3], v[8:9], off offset:256
	v_ashrrev_i32_e32 v199, 3, v162
	s_lshl_b32 s8, s3, 7
	v_add_u32_e32 v16, s31, v199
	s_add_u32 s8, s29, s8
	v_ashrrev_i32_e32 v17, 31, v16
	v_lshlrev_b32_e32 v72, 4, v162
	s_addc_u32 s9, s30, 0
	v_lshlrev_b64 v[16:17], 10, v[16:17]
	v_lshl_add_u64 v[12:13], v[4:5], 0, v[48:49]
	v_lshl_add_u64 v[16:17], s[8:9], 0, v[16:17]
	v_and_b32_e32 v50, 0x70, v72
	v_mov_b32_e32 v51, v173
	global_load_dwordx4 v[4:7], v[12:13], off offset:256
	v_lshl_add_u64 v[16:17], v[16:17], 0, v[50:51]
	global_load_dwordx4 v[8:11], v[8:9], off
	v_and_b32_e32 v20, 0xfffff0, v198
	global_load_dwordx4 v[12:15], v[12:13], off
	v_lshlrev_b32_e32 v21, 1, v198
	global_load_dwordx4 v[16:19], v[16:17], off
	v_and_or_b32 v20, v21, 8, v20
	v_lshrrev_b32_e32 v21, 1, v198
	v_lshrrev_b32_e32 v20, 1, v20
	v_bfe_u32 v22, v52, 5, 2
	v_and_b32_e32 v23, 3, v198
	v_or_b32_e32 v20, v20, v22
	v_and_or_b32 v21, v21, 4, v23
	v_lshlrev_b32_e32 v20, 9, v20
	v_lshlrev_b32_e32 v21, 6, v21
	v_and_b32_e32 v23, 48, v48
	v_or3_b32 v20, v20, v21, v23
	v_add_u32_e32 v200, 32, v198
	v_and_b32_e32 v24, 0xfffff0, v200
	v_lshlrev_b32_e32 v25, 1, v200
	v_add_u32_e32 v201, 0, v20
	v_and_or_b32 v24, v25, 8, v24
	s_waitcnt vmcnt(0)
	v_lshrrev_b32_e32 v24, 1, v24
	v_or_b32_e32 v22, v24, v22
	v_lshlrev_b32_e32 v22, 9, v22
	v_or3_b32 v21, v22, v21, v23
	v_add_u32_e32 v202, 0, v21
	s_add_i32 s31, 0, 0x10000
	v_and_b32_e32 v74, 63, v162
	v_mov_b32_e32 v77, 0xf149f2ca
	v_lshl_add_u64 v[180:181], s[6:7], 0, v[48:49]
	v_lshl_add_u64 v[182:183], s[8:9], 0, v[50:51]
	v_mov_b32_e32 v187, 0
	s_waitcnt vmcnt(4)
	ds_write_b128 v201, v[0:3]
	v_lshlrev_b32_e32 v0, 8, v198
	v_and_b32_e32 v1, 0xf0, v162
	v_bitop3_b32 v0, v48, v0, v1 bitop3:0xde
	v_add_u32_e32 v203, 0, v0
	v_lshlrev_b32_e32 v0, 8, v200
	v_bitop3_b32 v0, v48, v0, v1 bitop3:0xde
	v_add_u32_e32 v204, 0, v0
	v_lshlrev_b32_e32 v0, 7, v199
	v_and_b32_e32 v1, 0x70, v162
	v_bitop3_b32 v73, v50, v0, v1 bitop3:0xde
	v_add_u32_e32 v0, s31, v73
	v_add_u32_e32 v222, 0, v73
	s_waitcnt vmcnt(3)
	ds_write_b128 v202, v[4:7]
	v_add_u32_e32 v223, 0x12000, v222
	s_waitcnt vmcnt(2)
	ds_write_b128 v203, v[8:11] offset:32768
	v_lshlrev_b32_e32 v8, 8, v184
	v_and_b32_e32 v9, 0xf0, v72
	s_waitcnt vmcnt(1)
	ds_write_b128 v204, v[12:15] offset:32768
	s_waitcnt vmcnt(0)
	ds_write_b128 v0, v[16:19]
	v_bitop3_b32 v0, v172, v8, v9 bitop3:0xde
	v_add_u32_e32 v205, 0, v0
	s_waitcnt lgkmcnt(0)
	s_barrier
; #define SBAR() __builtin_amdgcn_sched_barrier(0)
; __device__ __forceinline__ int v_st(int k, int c) { const int kk = (k & ~0xC) | ((k & 4) << 1) | ((k & 8) >> 1); return ((kk >> 3) * 4 + (c >> 5)) * 512 + ((kk & 7) * 32 + (c & 31)) * 2; }
; __device__ __forceinline__ int v_rd_base(int lane) { return ((lane & 3) << 3) | (((lane >> 2) & 3) << 6) | (((lane >> 4) & 1) << 5) | (((lane >> 5) & 1) << 8); }
; #define SLOAD(j) do { const int r0_ = TROW(j); const bf16_t* a_ = KVh + (size_t)(r0_ + sr) * LDKV + sc; const bf16_t* b_ = KVh + (size_t)(r0_ + 32 + sr) * LDKV + sc; \
;     vs0 = ld8(a_ + 128); vs1 = ld8(b_ + 128); ks0 = ld8(a_); ks1 = ld8(b_); kp0 = ld8(KPh + (size_t)(r0_ + pr) * LDKP + pc); } while (0)
; #define SWRITE(b) do { *(bf16x8*)(V_lds + (b) * SHM_V + vst0) = vs0; *(bf16x8*)(V_lds + (b) * SHM_V + vst1) = vs1; const int kc = sc * 2; \
;     *(bf16x8*)(KN_lds + (b) * SHM_KN + KSWZ(sr, kc)) = ks0; *(bf16x8*)(KN_lds + (b) * SHM_KN + KSWZ(32 + sr, kc)) = ks1; \
;     *(bf16x8*)(KP_lds + (b) * SHM_KP + KPSWZ(pr, pc * 2)) = kp0; } while (0)
; #define SWAIT() asm volatile("s_waitcnt vmcnt(0)" ::: "memory")
; __device__ __forceinline__ void attn_unit(const bf16_t* __restrict__ Qb, const bf16_t* __restrict__ KV, const bf16_t* __restrict__ KP, bf16_t* __restrict__ Ob, ...
;     ...
;   const int sr = tid >> 4, sc = (tid & 15) * 8, vst0 = v_st(sr, sc), vst1 = v_st(32 + sr, sc);
;   const int pr = tid >> 3, pc = (tid & 7) * 8;
;   const int vb0 = (int)(uintptr_t)V_lds + v_rd_base(lane);
;   bf16x8 vs0, vs1, ks0, ks1, kp0;
;   const bf16_t* KVh = KV + h * 256; const bf16_t* KPh = KP + h * QKR;
;     ...
;   f32x16 pA0, pA1, pB0, pB1; float mnA, mnB, alA, alB; bf16x8 pa0, pa1, pa2, pa3;
;   SLOAD(0); SWAIT(); SWRITE(0); __syncthreads();
;   qkt(pA0, pA1, KN_lds, KP_lds, qr, r32, hi); partialSM(pA0, pA1, m_reg, mnA, alA);
;   SLOAD(1);
;   SWAIT(); SWRITE(1); __syncthreads();
;   for (int j = 1; j + 1 < NT; j += 2) {
;     SBAR(); qkt(pB0, pB1, KN_lds + SHM_KN, KP_lds + SHM_KP, qr, r32, hi);
;     finishSM(pA0, pA1, alA, l_reg, pa0, pa1, pa2, pa3); SBAR();
;     SLOAD(j + 1); SBAR();
;     pv_d0(o, vb0, pa0, pa1, pa2, pa3); partialSM(pB0, pB1, m_reg, mnB, alB);
;     __syncthreads(); SWAIT(); SWRITE(0);
;     RESC(alB); __syncthreads();
	s_movk_i32 s49, 0x1000
	s_waitcnt vmcnt(0)
	v_readfirstlane_b32 s40, v188
	s_nop 1
	s_lshr_b32 s40, s40, 6
	s_lshr_b32 s41, s40, 2
	v_and_b32_e32 v187, 0x3fffffc0, v188
	v_lshlrev_b32_e32 v179, 2, v187
	v_add_u32_e32 v179, 0x14000, v179
	v_lshl_add_u32 v186, v184, 2, v179
	v_and_b32_e32 v187, 63, v188
	v_cmp_gt_u32_e64 s[6:7], 32, v187
	s_add_i32 s31, s25, 0x4000
	s_lshl_b32 s44, s3, 9
	s_add_u32 s47, s27, s44
	s_addc_u32 s63, s28, 0
	s_lshl_b32 s44, s3, 7
	s_add_u32 s60, s29, s44
	s_addc_u32 s61, s30, 0
	v_lshrrev_b32_e32 v180, 4, v188
	v_lshlrev_b32_e32 v180, 12, v180
	v_and_b32_e32 v181, 15, v188
	v_lshl_or_b32 v180, v181, 4, v180
	v_lshrrev_b32_e32 v181, 3, v188
	v_lshlrev_b32_e32 v181, 10, v181
	v_and_b32_e32 v182, 7, v188
	v_lshl_or_b32 v181, v182, 4, v181
	v_lshlrev_b32_e32 v250, 8, v184
	v_and_b32_e32 v251, 15, v184
	v_lshlrev_b32_e32 v251, 4, v251
	v_or_b32_e32 v249, 0, v172
	v_xor_b32_e32 v249, v249, v251
	v_or_b32_e32 v249, v249, v250
	v_add_u32_e32 v160, 0x8000, v249
	v_or_b32_e32 v249, 32, v172
	v_xor_b32_e32 v249, v249, v251
	v_or_b32_e32 v249, v249, v250
	v_add_u32_e32 v161, 0x8000, v249
	v_or_b32_e32 v249, 64, v172
	v_xor_b32_e32 v249, v249, v251
	v_or_b32_e32 v249, v249, v250
	v_add_u32_e32 v162, 0x8000, v249
	v_or_b32_e32 v249, 96, v172
	v_xor_b32_e32 v249, v249, v251
	v_or_b32_e32 v249, v249, v250
	v_add_u32_e32 v163, 0x8000, v249
	v_or_b32_e32 v249, 128, v172
	v_xor_b32_e32 v249, v249, v251
	v_or_b32_e32 v249, v249, v250
	v_add_u32_e32 v164, 0x8000, v249
	v_or_b32_e32 v249, 160, v172
	v_xor_b32_e32 v249, v249, v251
	v_or_b32_e32 v249, v249, v250
	v_add_u32_e32 v165, 0x8000, v249
	v_or_b32_e32 v249, 192, v172
	v_xor_b32_e32 v249, v249, v251
	v_or_b32_e32 v249, v249, v250
	v_add_u32_e32 v166, 0x8000, v249
	v_or_b32_e32 v249, 224, v172
	v_xor_b32_e32 v249, v249, v251
	v_or_b32_e32 v249, v249, v250
	v_add_u32_e32 v167, 0x8000, v249
	v_lshlrev_b32_e32 v250, 7, v184
	v_lshrrev_b32_e32 v251, 1, v184
	v_and_b32_e32 v251, 7, v251
	v_lshlrev_b32_e32 v251, 4, v251
	v_or_b32_e32 v249, 0, v172
	v_xor_b32_e32 v249, v249, v251
	v_or_b32_e32 v249, v249, v250
	v_add_u32_e32 v168, 0x10000, v249
	v_or_b32_e32 v249, 32, v172
	v_xor_b32_e32 v249, v249, v251
	v_or_b32_e32 v249, v249, v250
	v_add_u32_e32 v169, 0x10000, v249
	v_or_b32_e32 v249, 64, v172
	v_xor_b32_e32 v249, v249, v251
	v_or_b32_e32 v249, v249, v250
	v_add_u32_e32 v170, 0x10000, v249
	v_or_b32_e32 v249, 96, v172
	v_xor_b32_e32 v249, v249, v251
	v_or_b32_e32 v249, v249, v250
	v_add_u32_e32 v171, 0x10000, v249
	v_and_b32_e32 v187, 63, v188
	v_lshlrev_b32_e32 v249, 3, v187
	v_lshlrev_b32_e32 v250, 4, v187
	v_and_b32_e32 v250, 0xc0, v250
	v_and_or_b32 v250, v249, 24, v250
	v_lshlrev_b32_e32 v251, 1, v187
	v_and_b32_e32 v251, 32, v251
	v_and_b32_e32 v249, 0x100, v249
	v_or3_b32 v174, v250, v251, v249
	v_mov_b32_e32 v244, v201
	v_mov_b32_e32 v245, v202
	v_add_u32_e32 v246, 0xc000, v203
	v_add_u32_e32 v247, 0xc000, v204
	v_add_u32_e32 v248, 0x12000, v222
	v_mov_b32_e32 v175, 0xf149f2ca
	v_mov_b32_e32 v176, 0
	v_mov_b32_e32 v0, 0
	v_mov_b32_e32 v1, 0
	v_mov_b32_e32 v2, 0
	v_mov_b32_e32 v3, 0
	v_mov_b32_e32 v4, 0
	v_mov_b32_e32 v5, 0
	v_mov_b32_e32 v6, 0
	v_mov_b32_e32 v7, 0
	v_mov_b32_e32 v8, 0
	v_mov_b32_e32 v9, 0
	v_mov_b32_e32 v10, 0
	v_mov_b32_e32 v11, 0
	v_mov_b32_e32 v12, 0
	v_mov_b32_e32 v13, 0
	v_mov_b32_e32 v14, 0
	v_mov_b32_e32 v15, 0
	v_mov_b32_e32 v16, 0
	v_mov_b32_e32 v17, 0
	v_mov_b32_e32 v18, 0
	v_mov_b32_e32 v19, 0
	v_mov_b32_e32 v20, 0
	v_mov_b32_e32 v21, 0
	v_mov_b32_e32 v22, 0
	v_mov_b32_e32 v23, 0
	v_mov_b32_e32 v24, 0
	v_mov_b32_e32 v25, 0
	v_mov_b32_e32 v26, 0
	v_mov_b32_e32 v27, 0
	v_mov_b32_e32 v28, 0
	v_mov_b32_e32 v29, 0
	v_mov_b32_e32 v30, 0
	v_mov_b32_e32 v31, 0
	v_mov_b32_e32 v32, 0
	v_mov_b32_e32 v33, 0
	v_mov_b32_e32 v34, 0
	v_mov_b32_e32 v35, 0
	v_mov_b32_e32 v36, 0
	v_mov_b32_e32 v37, 0
	v_mov_b32_e32 v38, 0
	v_mov_b32_e32 v39, 0
	v_mov_b32_e32 v40, 0
	v_mov_b32_e32 v41, 0
	v_mov_b32_e32 v42, 0
	v_mov_b32_e32 v43, 0
	v_mov_b32_e32 v44, 0
	v_mov_b32_e32 v45, 0
	v_mov_b32_e32 v46, 0
	v_mov_b32_e32 v47, 0
	v_mov_b32_e32 v48, 0
	v_mov_b32_e32 v49, 0
	v_mov_b32_e32 v50, 0
	v_mov_b32_e32 v51, 0
	v_mov_b32_e32 v52, 0
	v_mov_b32_e32 v53, 0
	v_mov_b32_e32 v54, 0
	v_mov_b32_e32 v55, 0
	v_mov_b32_e32 v56, 0
	v_mov_b32_e32 v57, 0
	v_mov_b32_e32 v58, 0
	v_mov_b32_e32 v59, 0
	v_mov_b32_e32 v60, 0
	v_mov_b32_e32 v61, 0
	v_mov_b32_e32 v62, 0
	v_mov_b32_e32 v63, 0
	v_mov_b32_e32 v144, 0
	v_mov_b32_e32 v145, 0
	v_mov_b32_e32 v146, 0
	v_mov_b32_e32 v147, 0
	v_mov_b32_e32 v148, 0
	v_mov_b32_e32 v149, 0
	v_mov_b32_e32 v150, 0
	v_mov_b32_e32 v151, 0
	v_mov_b32_e32 v152, 0
	v_mov_b32_e32 v153, 0
	v_mov_b32_e32 v154, 0
	v_mov_b32_e32 v155, 0
	v_mov_b32_e32 v156, 0
	v_mov_b32_e32 v157, 0
	v_mov_b32_e32 v158, 0
	v_mov_b32_e32 v159, 0
	s_mov_b32 s35, 0
	s_mov_b32 s11, 0
	s_add_i32 s36, s31, 64
	s_mov_b32 s37, s31
	s_lshl_b32 s44, s36, 12
	s_add_u32 s50, s47, s44
	s_addc_u32 s51, s63, 0
	s_add_u32 s52, s50, 0x20000
	s_addc_u32 s53, s51, 0
	s_lshl_b32 s44, s37, 12
	s_add_u32 s54, s47, s44
	s_addc_u32 s55, s63, 0
	s_add_u32 s56, s54, 0x20000
	s_addc_u32 s57, s55, 0
	s_lshl_b32 s44, s36, 10
	s_add_u32 s58, s60, s44
	s_addc_u32 s59, s61, 0
	global_load_dwordx4 v[232:235], v180, s[50:51]
	global_load_dwordx4 v[236:239], v180, s[52:53]
	global_load_dwordx4 v[224:227], v180, s[54:55] offset:256
	global_load_dwordx4 v[228:231], v180, s[56:57] offset:256
	global_load_dwordx4 v[240:243], v181, s[58:59]
	s_cmp_eq_u32 s41, 0
	s_cbranch_scc1 .Lpp_ga
	s_waitcnt vmcnt(0)
	ds_write_b128 v246, v[232:235]
	ds_write_b128 v247, v[236:239]
	ds_write_b128 v248, v[240:243]
	ds_write_b128 v244, v[224:227]
	ds_write_b128 v245, v[228:231]
	v_xor_b32_e32 v244, 0x4000, v244
	v_xor_b32_e32 v245, 0x4000, v245
	v_xor_b32_e32 v246, 0x4000, v246
	v_xor_b32_e32 v247, 0x4000, v247
	v_xor_b32_e32 v248, 0x2000, v248
	s_add_i32 s36, s35, 2
	s_min_u32 s36, s36, 67
	s_lshl_b32 s44, s36, 6
	s_add_i32 s45, s31, s44
	s_add_i32 s46, s24, s44
	s_add_i32 s46, s46, 0xffffff00
	s_cmp_lt_u32 s36, 4
	s_cselect_b32 s36, s45, s46
	s_add_i32 s37, s35, 1
	s_min_u32 s37, s37, 67
	s_lshl_b32 s44, s37, 6
	s_add_i32 s45, s31, s44
	s_add_i32 s46, s24, s44
	s_add_i32 s46, s46, 0xffffff00
	s_cmp_lt_u32 s37, 4
	s_cselect_b32 s37, s45, s46
	s_add_i32 s35, s35, 1
	s_lshl_b32 s44, s36, 12
	s_add_u32 s50, s47, s44
	s_addc_u32 s51, s63, 0
	s_add_u32 s52, s50, 0x20000
	s_addc_u32 s53, s51, 0
	s_lshl_b32 s44, s37, 12
	s_add_u32 s54, s47, s44
	s_addc_u32 s55, s63, 0
	s_add_u32 s56, s54, 0x20000
	s_addc_u32 s57, s55, 0
	s_lshl_b32 s44, s36, 10
	s_add_u32 s58, s60, s44
	s_addc_u32 s59, s61, 0
	global_load_dwordx4 v[232:235], v180, s[50:51]
	global_load_dwordx4 v[236:239], v180, s[52:53]
	global_load_dwordx4 v[224:227], v180, s[54:55] offset:256
	global_load_dwordx4 v[228:231], v180, s[56:57] offset:256
	global_load_dwordx4 v[240:243], v181, s[58:59]
	s_waitcnt lgkmcnt(0)
	s_barrier
; __device__ __forceinline__ void partialSM(f32x16& p0, f32x16& p1, float& m_reg, float& mn, float& alpha) {
;   constexpr float C = SCALE * 1.4426950408889634f;
;   float pmax = p0[0]; for (int r = 1; r < 16; ++r) pmax = fmaxf(pmax, p0[r]); for (int r = 0; r < 16; ++r) pmax = fmaxf(pmax, p1[r]);
;   { auto rr = __builtin_amdgcn_permlane32_swap(__float_as_uint(pmax), __float_as_uint(pmax), false, false);
;     pmax = fmaxf(__uint_as_float(rr[0]), __uint_as_float(rr[1])); }
;   if (__builtin_expect(__all(pmax - m_reg <= THR / SCALE), 1)) { mn = m_reg; alpha = 1.f; }
;   else { mn = fmaxf(m_reg, pmax); alpha = __builtin_amdgcn_exp2f((m_reg - mn) * C); m_reg = mn; }
;   float mnC = -mn * C;
;   for (int r = 0; r < 16; ++r) p0[r] = fmaf(p0[r], C, mnC); for (int r = 0; r < 16; ++r) p1[r] = fmaf(p1[r], C, mnC);
;   for (int r = 0; r < 16; ++r) p0[r] = __builtin_amdgcn_exp2f(p0[r]);
; }
; __device__ __forceinline__ void finishSM(f32x16& p0, f32x16& p1, float alpha, float& l_reg, bf16x8& pa0, bf16x8& pa1, bf16x8& pa2, bf16x8& pa3) {
;   for (int r = 0; r < 16; ++r) p1[r] = __builtin_amdgcn_exp2f(p1[r]);
;   float ps = 0; for (int r = 0; r < 16; ++r) ps += p0[r]; for (int r = 0; r < 16; ++r) ps += p1[r];
;   { auto rr = __builtin_amdgcn_permlane32_swap(__float_as_uint(ps), __float_as_uint(ps), false, false);
;     ps = __uint_as_float(rr[0]) + __uint_as_float(rr[1]); }
;   l_reg = l_reg * alpha + ps;
;     ...
;   PK4(p0, 0, pa0); PK4(p0, 8, pa1); PK4(p1, 0, pa2); PK4(p1, 8, pa3);
;     ...
; }
; __device__ __forceinline__ void qkt(f32x16& p0, f32x16& p1, const char* Kn, const char* Kp, const bf16x8* qr, int r32, int hi) {
;   p0 = f32x16{}; p1 = f32x16{};
; #pragma unroll
;   for (int d0 = 0; d0 < 8; ++d0) { int cb = (d0 * 16 + hi * 8) * 2;
;     bf16x8 b0 = *reinterpret_cast<const bf16x8*>(Kn + KSWZ(r32, cb));
;     bf16x8 b1 = *reinterpret_cast<const bf16x8*>(Kn + KSWZ(32 + r32, cb));
;     p0 = __builtin_amdgcn_mfma_f32_32x32x16_bf16(b0, qr[d0], p0, 0, 0, 0);
;     p1 = __builtin_amdgcn_mfma_f32_32x32x16_bf16(b1, qr[d0], p1, 0, 0, 0); }
; #pragma unroll
;   for (int d1 = 0; d1 < 4; ++d1) { int cb = (d1 * 16 + hi * 8) * 2;
;     bf16x8 b0 = *reinterpret_cast<const bf16x8*>(Kp + KPSWZ(r32, cb));
;     bf16x8 b1 = *reinterpret_cast<const bf16x8*>(Kp + KPSWZ(32 + r32, cb));
;     p0 = __builtin_amdgcn_mfma_f32_32x32x16_bf16(b0, qr[8 + d1], p0, 0, 0, 0);
.Lpp_ga:
	ds_read_b128 v[192:195], v160
	ds_read_b128 v[196:199], v160 offset:8192
	ds_read_b128 v[200:203], v161
	ds_read_b128 v[204:207], v161 offset:8192
	ds_read_b128 v[208:211], v162
	ds_read_b128 v[212:215], v162 offset:8192
	s_waitcnt lgkmcnt(5)
	v_mfma_f32_32x32x16_bf16 v[80:95], v[192:195], v[136:139], 0
	ds_read_b128 v[192:195], v163
	s_waitcnt lgkmcnt(5)
	v_mfma_f32_32x32x16_bf16 v[64:79], v[196:199], v[136:139], 0
	ds_read_b128 v[196:199], v163 offset:8192
	s_waitcnt lgkmcnt(5)
	v_mfma_f32_32x32x16_bf16 v[80:95], v[200:203], v[132:135], v[80:95]
	ds_read_b128 v[200:203], v164
	s_waitcnt lgkmcnt(5)
	v_mfma_f32_32x32x16_bf16 v[64:79], v[204:207], v[132:135], v[64:79]
	ds_read_b128 v[204:207], v164 offset:8192
	s_waitcnt lgkmcnt(5)
	v_mfma_f32_32x32x16_bf16 v[80:95], v[208:211], v[128:131], v[80:95]
	ds_read_b128 v[208:211], v165
	s_waitcnt lgkmcnt(5)
	v_mfma_f32_32x32x16_bf16 v[64:79], v[212:215], v[128:131], v[64:79]
	ds_read_b128 v[212:215], v165 offset:8192
	s_waitcnt lgkmcnt(5)
	v_mfma_f32_32x32x16_bf16 v[80:95], v[192:195], v[124:127], v[80:95]
	ds_read_b128 v[192:195], v166
	s_waitcnt lgkmcnt(5)
	v_mfma_f32_32x32x16_bf16 v[64:79], v[196:199], v[124:127], v[64:79]
	ds_read_b128 v[196:199], v166 offset:8192
	s_waitcnt lgkmcnt(5)
	v_mfma_f32_32x32x16_bf16 v[80:95], v[200:203], v[120:123], v[80:95]
	ds_read_b128 v[200:203], v167
	s_waitcnt lgkmcnt(5)
	v_mfma_f32_32x32x16_bf16 v[64:79], v[204:207], v[120:123], v[64:79]
	ds_read_b128 v[204:207], v167 offset:8192
	s_waitcnt lgkmcnt(5)
	v_mfma_f32_32x32x16_bf16 v[80:95], v[208:211], v[140:143], v[80:95]
	ds_read_b128 v[208:211], v168
	s_waitcnt lgkmcnt(5)
	v_mfma_f32_32x32x16_bf16 v[64:79], v[212:215], v[140:143], v[64:79]
	ds_read_b128 v[212:215], v168 offset:4096
	s_waitcnt lgkmcnt(5)
	v_mfma_f32_32x32x16_bf16 v[80:95], v[192:195], v[116:119], v[80:95]
	ds_read_b128 v[192:195], v169
	s_waitcnt lgkmcnt(5)
	v_mfma_f32_32x32x16_bf16 v[64:79], v[196:199], v[116:119], v[64:79]
	ds_read_b128 v[196:199], v169 offset:4096
	s_waitcnt lgkmcnt(5)
	v_mfma_f32_32x32x16_bf16 v[80:95], v[200:203], v[112:115], v[80:95]
	ds_read_b128 v[200:203], v170
	s_waitcnt lgkmcnt(5)
	v_mfma_f32_32x32x16_bf16 v[64:79], v[204:207], v[112:115], v[64:79]
	ds_read_b128 v[204:207], v170 offset:4096
	s_waitcnt lgkmcnt(5)
	v_mfma_f32_32x32x16_bf16 v[80:95], v[208:211], v[108:111], v[80:95]
	ds_read_b128 v[208:211], v171
	s_waitcnt lgkmcnt(5)
	v_mfma_f32_32x32x16_bf16 v[64:79], v[212:215], v[108:111], v[64:79]
	ds_read_b128 v[212:215], v171 offset:4096
	s_waitcnt lgkmcnt(5)
	v_mfma_f32_32x32x16_bf16 v[80:95], v[192:195], v[104:107], v[80:95]
	s_waitcnt lgkmcnt(4)
	v_mfma_f32_32x32x16_bf16 v[64:79], v[196:199], v[104:107], v[64:79]
	s_waitcnt lgkmcnt(3)
	v_mfma_f32_32x32x16_bf16 v[80:95], v[200:203], v[100:103], v[80:95]
	s_waitcnt lgkmcnt(2)
	v_mfma_f32_32x32x16_bf16 v[64:79], v[204:207], v[100:103], v[64:79]
	s_waitcnt lgkmcnt(1)
	v_mfma_f32_32x32x16_bf16 v[80:95], v[208:211], v[96:99], v[80:95]
	s_waitcnt lgkmcnt(0)
	v_mfma_f32_32x32x16_bf16 v[64:79], v[212:215], v[96:99], v[64:79]
	s_barrier
.Lpp_loop:
	s_waitcnt vmcnt(0)
	ds_write_b128 v246, v[232:235]
	ds_write_b128 v247, v[236:239]
	ds_write_b128 v248, v[240:243]
	ds_write_b128 v244, v[224:227]
	ds_write_b128 v245, v[228:231]
	v_xor_b32_e32 v244, 0x4000, v244
	v_xor_b32_e32 v245, 0x4000, v245
	v_xor_b32_e32 v246, 0x4000, v246
	v_xor_b32_e32 v247, 0x4000, v247
	v_xor_b32_e32 v248, 0x2000, v248
	s_add_i32 s36, s35, 2
	s_min_u32 s36, s36, 67
	s_lshl_b32 s44, s36, 6
	s_add_i32 s45, s31, s44
	s_add_i32 s46, s24, s44
	s_add_i32 s46, s46, 0xffffff00
	s_cmp_lt_u32 s36, 4
	s_cselect_b32 s36, s45, s46
	s_add_i32 s37, s35, 1
	s_min_u32 s37, s37, 67
	s_lshl_b32 s44, s37, 6
	s_add_i32 s45, s31, s44
	s_add_i32 s46, s24, s44
	s_add_i32 s46, s46, 0xffffff00
	s_cmp_lt_u32 s37, 4
	s_cselect_b32 s37, s45, s46
	s_add_i32 s35, s35, 1
	s_lshl_b32 s44, s36, 12
	s_add_u32 s50, s47, s44
	s_addc_u32 s51, s63, 0
	s_add_u32 s52, s50, 0x20000
	s_addc_u32 s53, s51, 0
	s_lshl_b32 s44, s37, 12
	s_add_u32 s54, s47, s44
	s_addc_u32 s55, s63, 0
	s_add_u32 s56, s54, 0x20000
	s_addc_u32 s57, s55, 0
	s_lshl_b32 s44, s36, 10
	s_add_u32 s58, s60, s44
	s_addc_u32 s59, s61, 0
	global_load_dwordx4 v[232:235], v180, s[50:51]
	global_load_dwordx4 v[236:239], v180, s[52:53]
	global_load_dwordx4 v[224:227], v180, s[54:55] offset:256
	global_load_dwordx4 v[228:231], v180, s[56:57] offset:256
	global_load_dwordx4 v[240:243], v181, s[58:59]
	v_max3_f32 v250, v80, v81, v82
	v_max3_f32 v250, v250, v83, v84
	v_max3_f32 v250, v250, v85, v86
	v_max3_f32 v250, v250, v87, v88
	v_max3_f32 v250, v250, v89, v90
	v_max3_f32 v250, v250, v91, v92
	v_max3_f32 v250, v250, v93, v94
	v_max3_f32 v250, v250, v95, v64
	v_max3_f32 v250, v250, v65, v66
	v_max3_f32 v250, v250, v67, v68
	v_max3_f32 v250, v250, v69, v70
	v_max3_f32 v250, v250, v71, v72
	v_max3_f32 v250, v250, v73, v74
	v_max3_f32 v250, v250, v75, v76
	v_max3_f32 v250, v250, v77, v78
	v_max3_f32 v250, v250, v79, v79
	v_mov_b32_e32 v251, v250
	s_nop 1
	v_permlane32_swap_b32_e32 v250, v251
	v_max_f32_e32 v250, v250, v251
	v_sub_f32_e32 v251, v250, v175
	v_cmp_ge_f32_e32 vcc, s33, v251
	v_max_f32_e32 v249, v175, v250
	v_sub_f32_e32 v251, v175, v249
	v_mul_f32_e32 v251, 0x3dd53b94, v251
	v_exp_f32_e32 v251, v251
	s_nop 1
	s_cmp_eq_u64 vcc, exec
	s_cselect_b64 s[8:9], -1, 0
	v_cndmask_b32_e64 v177, v251, 1.0, s[8:9]
	v_cndmask_b32_e64 v175, v249, v175, s[8:9]
	v_cmp_gt_f32_e32 vcc, 1.0, v177
	s_nop 4
	s_cbranch_vccz .Lpp_nr_a
; __device__ __forceinline__ void partialSM(f32x16& p0, f32x16& p1, float& m_reg, float& mn, float& alpha) {
;   constexpr float C = SCALE * 1.4426950408889634f;
;   float pmax = p0[0]; for (int r = 1; r < 16; ++r) pmax = fmaxf(pmax, p0[r]); for (int r = 0; r < 16; ++r) pmax = fmaxf(pmax, p1[r]);
;   { auto rr = __builtin_amdgcn_permlane32_swap(__float_as_uint(pmax), __float_as_uint(pmax), false, false);
;     pmax = fmaxf(__uint_as_float(rr[0]), __uint_as_float(rr[1])); }
;   if (__builtin_expect(__all(pmax - m_reg <= THR / SCALE), 1)) { mn = m_reg; alpha = 1.f; }
;   else { mn = fmaxf(m_reg, pmax); alpha = __builtin_amdgcn_exp2f((m_reg - mn) * C); m_reg = mn; }
;   float mnC = -mn * C;
;   for (int r = 0; r < 16; ++r) p0[r] = fmaf(p0[r], C, mnC); for (int r = 0; r < 16; ++r) p1[r] = fmaf(p1[r], C, mnC);
;   for (int r = 0; r < 16; ++r) p0[r] = __builtin_amdgcn_exp2f(p0[r]);
; }
; __device__ __forceinline__ void finishSM(f32x16& p0, f32x16& p1, float alpha, float& l_reg, bf16x8& pa0, bf16x8& pa1, bf16x8& pa2, bf16x8& pa3) {
;   for (int r = 0; r < 16; ++r) p1[r] = __builtin_amdgcn_exp2f(p1[r]);
;   float ps = 0; for (int r = 0; r < 16; ++r) ps += p0[r]; for (int r = 0; r < 16; ++r) ps += p1[r];
;   { auto rr = __builtin_amdgcn_permlane32_swap(__float_as_uint(ps), __float_as_uint(ps), false, false);
;     ps = __uint_as_float(rr[0]) + __uint_as_float(rr[1]); }
;   l_reg = l_reg * alpha + ps;
;     ...
;   PK4(p0, 0, pa0); PK4(p0, 8, pa1); PK4(p1, 0, pa2); PK4(p1, 8, pa3);
;     ...
; }
	s_and_saveexec_b64 s[42:43], s[6:7]
	ds_write_b32 v186, v177 offset:128
	s_or_b64 exec, exec, s[42:43]
	s_waitcnt lgkmcnt(0)
	v_add_u32_e32 v187, v179, v172
	ds_read_b128 v[192:195], v187 offset:128
	ds_read_b128 v[196:199], v187 offset:160
	ds_read_b128 v[200:203], v187 offset:192
	ds_read_b128 v[204:207], v187 offset:224
	s_waitcnt lgkmcnt(0)
	v_pk_mul_f32 v[0:1], v[0:1], v[192:193]
	v_pk_mul_f32 v[2:3], v[2:3], v[194:195]
	v_pk_mul_f32 v[4:5], v[4:5], v[196:197]
	v_pk_mul_f32 v[6:7], v[6:7], v[198:199]
	v_pk_mul_f32 v[8:9], v[8:9], v[200:201]
	v_pk_mul_f32 v[10:11], v[10:11], v[202:203]
	v_pk_mul_f32 v[12:13], v[12:13], v[204:205]
	v_pk_mul_f32 v[14:15], v[14:15], v[206:207]
	v_pk_mul_f32 v[48:49], v[48:49], v[192:193]
	v_pk_mul_f32 v[50:51], v[50:51], v[194:195]
	v_pk_mul_f32 v[52:53], v[52:53], v[196:197]
	v_pk_mul_f32 v[54:55], v[54:55], v[198:199]
	v_pk_mul_f32 v[56:57], v[56:57], v[200:201]
	v_pk_mul_f32 v[58:59], v[58:59], v[202:203]
	v_pk_mul_f32 v[60:61], v[60:61], v[204:205]
	v_pk_mul_f32 v[62:63], v[62:63], v[206:207]
	v_pk_mul_f32 v[32:33], v[32:33], v[192:193]
	v_pk_mul_f32 v[34:35], v[34:35], v[194:195]
	v_pk_mul_f32 v[36:37], v[36:37], v[196:197]
	v_pk_mul_f32 v[38:39], v[38:39], v[198:199]
	v_pk_mul_f32 v[40:41], v[40:41], v[200:201]
	v_pk_mul_f32 v[42:43], v[42:43], v[202:203]
	v_pk_mul_f32 v[44:45], v[44:45], v[204:205]
	v_pk_mul_f32 v[46:47], v[46:47], v[206:207]
	v_pk_mul_f32 v[16:17], v[16:17], v[192:193]
	v_pk_mul_f32 v[18:19], v[18:19], v[194:195]
	v_pk_mul_f32 v[20:21], v[20:21], v[196:197]
	v_pk_mul_f32 v[22:23], v[22:23], v[198:199]
	v_pk_mul_f32 v[24:25], v[24:25], v[200:201]
	v_pk_mul_f32 v[26:27], v[26:27], v[202:203]
	v_pk_mul_f32 v[28:29], v[28:29], v[204:205]
	v_pk_mul_f32 v[30:31], v[30:31], v[206:207]
.Lpp_nr_a:
	v_mul_f32_e32 v251, 0xbdd53b94, v175
	v_fmamk_f32 v80, v80, 0x3dd53b94, v251
	v_fmamk_f32 v81, v81, 0x3dd53b94, v251
	v_fmamk_f32 v82, v82, 0x3dd53b94, v251
	v_fmamk_f32 v83, v83, 0x3dd53b94, v251
	v_fmamk_f32 v84, v84, 0x3dd53b94, v251
	v_fmamk_f32 v85, v85, 0x3dd53b94, v251
	v_fmamk_f32 v86, v86, 0x3dd53b94, v251
	v_fmamk_f32 v87, v87, 0x3dd53b94, v251
	v_fmamk_f32 v88, v88, 0x3dd53b94, v251
	v_fmamk_f32 v89, v89, 0x3dd53b94, v251
	v_fmamk_f32 v90, v90, 0x3dd53b94, v251
	v_fmamk_f32 v91, v91, 0x3dd53b94, v251
	v_fmamk_f32 v92, v92, 0x3dd53b94, v251
	v_fmamk_f32 v93, v93, 0x3dd53b94, v251
	v_fmamk_f32 v94, v94, 0x3dd53b94, v251
	v_fmamk_f32 v95, v95, 0x3dd53b94, v251
	v_fmamk_f32 v64, v64, 0x3dd53b94, v251
	v_fmamk_f32 v65, v65, 0x3dd53b94, v251
	v_fmamk_f32 v66, v66, 0x3dd53b94, v251
	v_fmamk_f32 v67, v67, 0x3dd53b94, v251
	v_fmamk_f32 v68, v68, 0x3dd53b94, v251
	v_fmamk_f32 v69, v69, 0x3dd53b94, v251
	v_fmamk_f32 v70, v70, 0x3dd53b94, v251
	v_fmamk_f32 v71, v71, 0x3dd53b94, v251
	v_fmamk_f32 v72, v72, 0x3dd53b94, v251
	v_fmamk_f32 v73, v73, 0x3dd53b94, v251
	v_fmamk_f32 v74, v74, 0x3dd53b94, v251
	v_fmamk_f32 v75, v75, 0x3dd53b94, v251
	v_fmamk_f32 v76, v76, 0x3dd53b94, v251
	v_fmamk_f32 v77, v77, 0x3dd53b94, v251
	v_fmamk_f32 v78, v78, 0x3dd53b94, v251
	v_fmamk_f32 v79, v79, 0x3dd53b94, v251
	v_exp_f32_e32 v80, v80
	v_exp_f32_e32 v81, v81
	v_exp_f32_e32 v82, v82
	v_exp_f32_e32 v83, v83
	v_exp_f32_e32 v84, v84
	v_exp_f32_e32 v85, v85
	v_exp_f32_e32 v86, v86
	v_exp_f32_e32 v87, v87
	v_exp_f32_e32 v88, v88
	v_exp_f32_e32 v89, v89
	v_exp_f32_e32 v90, v90
	v_exp_f32_e32 v91, v91
	v_exp_f32_e32 v92, v92
	v_exp_f32_e32 v93, v93
	v_exp_f32_e32 v94, v94
	v_exp_f32_e32 v95, v95
	v_exp_f32_e32 v64, v64
	v_exp_f32_e32 v65, v65
	v_exp_f32_e32 v66, v66
	v_exp_f32_e32 v67, v67
	v_exp_f32_e32 v68, v68
	v_exp_f32_e32 v69, v69
	v_exp_f32_e32 v70, v70
	v_exp_f32_e32 v71, v71
	v_exp_f32_e32 v72, v72
	v_exp_f32_e32 v73, v73
	v_exp_f32_e32 v74, v74
	v_exp_f32_e32 v75, v75
	v_exp_f32_e32 v76, v76
	v_exp_f32_e32 v77, v77
	v_exp_f32_e32 v78, v78
	v_exp_f32_e32 v79, v79
	s_nop 0
	v_add_f32_e32 v249, v80, v81
	v_add_f32_e32 v249, v82, v249
	v_add_f32_e32 v249, v83, v249
	v_add_f32_e32 v249, v84, v249
	v_add_f32_e32 v249, v85, v249
	v_add_f32_e32 v249, v86, v249
	v_add_f32_e32 v249, v87, v249
	v_add_f32_e32 v249, v88, v249
	v_add_f32_e32 v249, v89, v249
	v_add_f32_e32 v249, v90, v249
	v_add_f32_e32 v249, v91, v249
	v_add_f32_e32 v249, v92, v249
	v_add_f32_e32 v249, v93, v249
	v_add_f32_e32 v249, v94, v249
	v_add_f32_e32 v249, v95, v249
	v_add_f32_e32 v249, v64, v249
	v_add_f32_e32 v249, v65, v249
	v_add_f32_e32 v249, v66, v249
	v_add_f32_e32 v249, v67, v249
	v_add_f32_e32 v249, v68, v249
	v_add_f32_e32 v249, v69, v249
	v_add_f32_e32 v249, v70, v249
	v_add_f32_e32 v249, v71, v249
	v_add_f32_e32 v249, v72, v249
	v_add_f32_e32 v249, v73, v249
	v_add_f32_e32 v249, v74, v249
	v_add_f32_e32 v249, v75, v249
	v_add_f32_e32 v249, v76, v249
	v_add_f32_e32 v249, v77, v249
	v_add_f32_e32 v249, v78, v249
	v_add_f32_e32 v249, v79, v249
	v_mov_b32_e32 v250, v249
	s_nop 1
	v_permlane32_swap_b32_e32 v249, v250
	v_add_f32_e32 v249, v249, v250
	v_fma_f32 v176, v176, v177, v249
	v_cvt_pk_bf16_f32 v144, v80, v81
	v_cvt_pk_bf16_f32 v145, v82, v83
	v_cvt_pk_bf16_f32 v146, v84, v85
	v_cvt_pk_bf16_f32 v147, v86, v87
	v_cvt_pk_bf16_f32 v148, v88, v89
	v_cvt_pk_bf16_f32 v149, v90, v91
	v_cvt_pk_bf16_f32 v150, v92, v93
	v_cvt_pk_bf16_f32 v151, v94, v95
	v_cvt_pk_bf16_f32 v152, v64, v65
	v_cvt_pk_bf16_f32 v153, v66, v67
	v_cvt_pk_bf16_f32 v154, v68, v69
	v_cvt_pk_bf16_f32 v155, v70, v71
	v_cvt_pk_bf16_f32 v156, v72, v73
	v_cvt_pk_bf16_f32 v157, v74, v75
	v_cvt_pk_bf16_f32 v158, v76, v77
	v_cvt_pk_bf16_f32 v159, v78, v79
	s_nop 1
	v_permlane32_swap_b32_e32 v144, v146
	v_permlane32_swap_b32_e32 v145, v147
	v_permlane32_swap_b32_e32 v148, v150
	v_permlane32_swap_b32_e32 v149, v151
	v_permlane32_swap_b32_e32 v152, v154
	v_permlane32_swap_b32_e32 v153, v155
	v_permlane32_swap_b32_e32 v156, v158
	v_permlane32_swap_b32_e32 v157, v159
	s_waitcnt lgkmcnt(0)
	s_barrier
; __device__ __forceinline__ void qkt(f32x16& p0, f32x16& p1, const char* Kn, const char* Kp, const bf16x8* qr, int r32, int hi) {
;   p0 = f32x16{}; p1 = f32x16{};
; #pragma unroll
;   for (int d0 = 0; d0 < 8; ++d0) { int cb = (d0 * 16 + hi * 8) * 2;
;     bf16x8 b0 = *reinterpret_cast<const bf16x8*>(Kn + KSWZ(r32, cb));
;     bf16x8 b1 = *reinterpret_cast<const bf16x8*>(Kn + KSWZ(32 + r32, cb));
;     p0 = __builtin_amdgcn_mfma_f32_32x32x16_bf16(b0, qr[d0], p0, 0, 0, 0);
;     p1 = __builtin_amdgcn_mfma_f32_32x32x16_bf16(b1, qr[d0], p1, 0, 0, 0); }
; #pragma unroll
;   for (int d1 = 0; d1 < 4; ++d1) { int cb = (d1 * 16 + hi * 8) * 2;
;     bf16x8 b0 = *reinterpret_cast<const bf16x8*>(Kp + KPSWZ(r32, cb));
;     bf16x8 b1 = *reinterpret_cast<const bf16x8*>(Kp + KPSWZ(32 + r32, cb));
;     p0 = __builtin_amdgcn_mfma_f32_32x32x16_bf16(b0, qr[8 + d1], p0, 0, 0, 0);
;     p1 = __builtin_amdgcn_mfma_f32_32x32x16_bf16(b1, qr[8 + d1], p1, 0, 0, 0); }
; }
; __device__ __forceinline__ int v_st(int k, int c) { const int kk = (k & ~0xC) | ((k & 4) << 1) | ((k & 8) >> 1); return ((kk >> 3) * 4 + (c >> 5)) * 512 + ((kk & 7) * 32 + (c & 31)) * 2; }
; __device__ __forceinline__ int v_rd_base(int lane) { return ((lane & 3) << 3) | (((lane >> 2) & 3) << 6) | (((lane >> 4) & 1) << 5) | (((lane >> 5) & 1) << 8); }
; template <int OFF> __device__ __forceinline__ s16x4 tr_read(int vb) {
;   s16x4 r; asm volatile("ds_read_b64_tr_b16 %0, %1 offset:%2" : "=&v"(r) : "v"(vb), "i"(OFF) : "memory"); return r;
; }
; template <int D0> __device__ __forceinline__ void pv_one(f32x16& od, int vb, bf16x8 pa0, bf16x8 pa1, bf16x8 pa2, bf16x8 pa3) {
;   const s16x4 l0 = tr_read<v_rd_off(D0, 0, 0)>(vb), h0 = tr_read<v_rd_off(D0, 0, 1)>(vb), l1 = tr_read<v_rd_off(D0, 1, 0)>(vb), h1 = tr_read<v_rd_off(D0, 1, 1)>(vb);
;   const s16x4 l2 = tr_read<v_rd_off(D0, 2, 0)>(vb), h2 = tr_read<v_rd_off(D0, 2, 1)>(vb), l3 = tr_read<v_rd_off(D0, 3, 0)>(vb), h3 = tr_read<v_rd_off(D0, 3, 1)>(vb);
;   asm volatile("s_waitcnt lgkmcnt(0)" ::: "memory"); SBAR();
;     ...
;   od = __builtin_amdgcn_mfma_f32_32x32x16_bf16(pa0, PK(l0, h0), od, 0, 0, 0);
;   od = __builtin_amdgcn_mfma_f32_32x32x16_bf16(pa1, PK(l1, h1), od, 0, 0, 0);
;   od = __builtin_amdgcn_mfma_f32_32x32x16_bf16(pa2, PK(l2, h2), od, 0, 0, 0);
;   od = __builtin_amdgcn_mfma_f32_32x32x16_bf16(pa3, PK(l3, h3), od, 0, 0, 0);
;     ...
; }
	s_add_i32 s11, s11, 1
	ds_read_b128 v[192:195], v160 offset:16384
	ds_read_b128 v[196:199], v160 offset:24576
	ds_read_b128 v[200:203], v161 offset:16384
	ds_read_b128 v[204:207], v161 offset:24576
	ds_read_b128 v[208:211], v162 offset:16384
	ds_read_b128 v[212:215], v162 offset:24576
	ds_read_b64_tr_b16 v[216:217], v174 offset:0
	ds_read_b64_tr_b16 v[218:219], v174 offset:2048
	ds_read_b64_tr_b16 v[220:221], v174 offset:4096
	ds_read_b64_tr_b16 v[222:223], v174 offset:6144
	s_waitcnt lgkmcnt(9)
	v_mfma_f32_32x32x16_bf16 v[80:95], v[192:195], v[136:139], 0
	ds_read_b128 v[192:195], v163 offset:16384
	s_waitcnt lgkmcnt(9)
	v_mfma_f32_32x32x16_bf16 v[64:79], v[196:199], v[136:139], 0
	ds_read_b128 v[196:199], v163 offset:24576
	s_waitcnt lgkmcnt(9)
	v_mfma_f32_32x32x16_bf16 v[80:95], v[200:203], v[132:135], v[80:95]
	ds_read_b128 v[200:203], v164 offset:16384
	s_waitcnt lgkmcnt(9)
	v_mfma_f32_32x32x16_bf16 v[64:79], v[204:207], v[132:135], v[64:79]
	ds_read_b128 v[204:207], v164 offset:24576
	s_waitcnt lgkmcnt(9)
	v_mfma_f32_32x32x16_bf16 v[80:95], v[208:211], v[128:131], v[80:95]
	ds_read_b128 v[208:211], v165 offset:16384
	s_waitcnt lgkmcnt(9)
	v_mfma_f32_32x32x16_bf16 v[64:79], v[212:215], v[128:131], v[64:79]
	ds_read_b128 v[212:215], v165 offset:24576
	s_waitcnt lgkmcnt(5)
	v_mfma_f32_32x32x16_bf16 v[80:95], v[192:195], v[124:127], v[80:95]
	ds_read_b128 v[192:195], v166 offset:16384
	s_waitcnt lgkmcnt(5)
	v_mfma_f32_32x32x16_bf16 v[64:79], v[196:199], v[124:127], v[64:79]
	ds_read_b128 v[196:199], v166 offset:24576
	s_waitcnt lgkmcnt(5)
	v_mfma_f32_32x32x16_bf16 v[80:95], v[200:203], v[120:123], v[80:95]
	ds_read_b128 v[200:203], v167 offset:16384
	s_waitcnt lgkmcnt(5)
	v_mfma_f32_32x32x16_bf16 v[64:79], v[204:207], v[120:123], v[64:79]
	ds_read_b128 v[204:207], v167 offset:24576
	s_waitcnt lgkmcnt(5)
	v_mfma_f32_32x32x16_bf16 v[80:95], v[208:211], v[140:143], v[80:95]
	ds_read_b128 v[208:211], v168 offset:8192
	s_waitcnt lgkmcnt(5)
	v_mfma_f32_32x32x16_bf16 v[64:79], v[212:215], v[140:143], v[64:79]
	ds_read_b128 v[212:215], v168 offset:12288
	s_waitcnt lgkmcnt(5)
	v_mfma_f32_32x32x16_bf16 v[80:95], v[192:195], v[116:119], v[80:95]
	ds_read_b128 v[192:195], v169 offset:8192
	s_waitcnt lgkmcnt(5)
	v_mfma_f32_32x32x16_bf16 v[64:79], v[196:199], v[116:119], v[64:79]
	ds_read_b128 v[196:199], v169 offset:12288
	s_waitcnt lgkmcnt(5)
	v_mfma_f32_32x32x16_bf16 v[80:95], v[200:203], v[112:115], v[80:95]
	ds_read_b128 v[200:203], v170 offset:8192
	s_waitcnt lgkmcnt(5)
	v_mfma_f32_32x32x16_bf16 v[64:79], v[204:207], v[112:115], v[64:79]
	ds_read_b128 v[204:207], v170 offset:12288
	s_waitcnt lgkmcnt(5)
	v_mfma_f32_32x32x16_bf16 v[80:95], v[208:211], v[108:111], v[80:95]
	ds_read_b128 v[208:211], v171 offset:8192
	s_waitcnt lgkmcnt(5)
	v_mfma_f32_32x32x16_bf16 v[64:79], v[212:215], v[108:111], v[64:79]
	ds_read_b128 v[212:215], v171 offset:12288
	s_waitcnt lgkmcnt(5)
	v_mfma_f32_32x32x16_bf16 v[80:95], v[192:195], v[104:107], v[80:95]
	ds_read_b64_tr_b16 v[192:193], v174 offset:8192
	ds_read_b64_tr_b16 v[194:195], v174 offset:10240
	s_waitcnt lgkmcnt(6)
	v_mfma_f32_32x32x16_bf16 v[64:79], v[196:199], v[104:107], v[64:79]
	ds_read_b64_tr_b16 v[196:197], v174 offset:12288
	ds_read_b64_tr_b16 v[198:199], v174 offset:14336
	s_waitcnt lgkmcnt(7)
	v_mfma_f32_32x32x16_bf16 v[80:95], v[200:203], v[100:103], v[80:95]
	ds_read_b64_tr_b16 v[200:201], v174 offset:512
	ds_read_b64_tr_b16 v[202:203], v174 offset:2560
	s_waitcnt lgkmcnt(8)
	v_mfma_f32_32x32x16_bf16 v[64:79], v[204:207], v[100:103], v[64:79]
	ds_read_b64_tr_b16 v[204:205], v174 offset:4608
	ds_read_b64_tr_b16 v[206:207], v174 offset:6656
	s_waitcnt lgkmcnt(9)
	v_mfma_f32_32x32x16_bf16 v[80:95], v[208:211], v[96:99], v[80:95]
	ds_read_b64_tr_b16 v[208:209], v174 offset:8704
	ds_read_b64_tr_b16 v[210:211], v174 offset:10752
	s_waitcnt lgkmcnt(10)
	v_mfma_f32_32x32x16_bf16 v[64:79], v[212:215], v[96:99], v[64:79]
	ds_read_b64_tr_b16 v[212:213], v174 offset:12800
	ds_read_b64_tr_b16 v[214:215], v174 offset:14848
	s_waitcnt lgkmcnt(15)
	v_mfma_f32_32x32x16_bf16 v[0:15], v[144:147], v[216:219], v[0:15]
	ds_read_b64_tr_b16 v[216:217], v174 offset:1024
	ds_read_b64_tr_b16 v[218:219], v174 offset:3072
	s_waitcnt lgkmcnt(15)
	v_mfma_f32_32x32x16_bf16 v[0:15], v[148:151], v[220:223], v[0:15]
	ds_read_b64_tr_b16 v[220:221], v174 offset:5120
	ds_read_b64_tr_b16 v[222:223], v174 offset:7168
	s_waitcnt lgkmcnt(14)
	v_mfma_f32_32x32x16_bf16 v[0:15], v[152:155], v[192:195], v[0:15]
	ds_read_b64_tr_b16 v[192:193], v174 offset:9216
	ds_read_b64_tr_b16 v[194:195], v174 offset:11264
	s_waitcnt lgkmcnt(14)
	v_mfma_f32_32x32x16_bf16 v[0:15], v[156:159], v[196:199], v[0:15]
	ds_read_b64_tr_b16 v[196:197], v174 offset:13312
	ds_read_b64_tr_b16 v[198:199], v174 offset:15360
	s_waitcnt lgkmcnt(14)
	v_mfma_f32_32x32x16_bf16 v[48:63], v[144:147], v[200:203], v[48:63]
	ds_read_b64_tr_b16 v[200:201], v174 offset:1536
	ds_read_b64_tr_b16 v[202:203], v174 offset:3584
	s_waitcnt lgkmcnt(14)
	v_mfma_f32_32x32x16_bf16 v[48:63], v[148:151], v[204:207], v[48:63]
	ds_read_b64_tr_b16 v[204:205], v174 offset:5632
	ds_read_b64_tr_b16 v[206:207], v174 offset:7680
	s_waitcnt lgkmcnt(14)
	v_mfma_f32_32x32x16_bf16 v[48:63], v[152:155], v[208:211], v[48:63]
	ds_read_b64_tr_b16 v[208:209], v174 offset:9728
	ds_read_b64_tr_b16 v[210:211], v174 offset:11776
	s_waitcnt lgkmcnt(14)
	v_mfma_f32_32x32x16_bf16 v[48:63], v[156:159], v[212:215], v[48:63]
	ds_read_b64_tr_b16 v[212:213], v174 offset:13824
	ds_read_b64_tr_b16 v[214:215], v174 offset:15872
	s_waitcnt lgkmcnt(14)
	v_mfma_f32_32x32x16_bf16 v[32:47], v[144:147], v[216:219], v[32:47]
	s_waitcnt lgkmcnt(12)
	v_mfma_f32_32x32x16_bf16 v[32:47], v[148:151], v[220:223], v[32:47]
	s_waitcnt lgkmcnt(10)
	v_mfma_f32_32x32x16_bf16 v[32:47], v[152:155], v[192:195], v[32:47]
	s_waitcnt lgkmcnt(8)
	v_mfma_f32_32x32x16_bf16 v[32:47], v[156:159], v[196:199], v[32:47]
	s_waitcnt lgkmcnt(6)
	v_mfma_f32_32x32x16_bf16 v[16:31], v[144:147], v[200:203], v[16:31]
	s_waitcnt lgkmcnt(4)
	v_mfma_f32_32x32x16_bf16 v[16:31], v[148:151], v[204:207], v[16:31]
	s_waitcnt lgkmcnt(2)
	v_mfma_f32_32x32x16_bf16 v[16:31], v[152:155], v[208:211], v[16:31]
	s_waitcnt lgkmcnt(0)
	v_mfma_f32_32x32x16_bf16 v[16:31], v[156:159], v[212:215], v[16:31]
	s_barrier
; #define SBAR() __builtin_amdgcn_sched_barrier(0)
; #define SLOAD(j) do { const int r0_ = TROW(j); const bf16_t* a_ = KVh + (size_t)(r0_ + sr) * LDKV + sc; const bf16_t* b_ = KVh + (size_t)(r0_ + 32 + sr) * LDKV + sc; \
;     vs0 = ld8(a_ + 128); vs1 = ld8(b_ + 128); ks0 = ld8(a_); ks1 = ld8(b_); kp0 = ld8(KPh + (size_t)(r0_ + pr) * LDKP + pc); } while (0)
; #define SWAIT() asm volatile("s_waitcnt vmcnt(0)" ::: "memory")
; #define RESC(a) do { if (__any((a) < 1.f)) { if (hi == 0) al_l[r32] = (a); asm volatile("s_waitcnt lgkmcnt(0)" ::: "memory"); \
;     for (int d = 0; d < 4; ++d) for (int r = 0; r < 16; ++r) o[d][r] *= al_l[crow(r, hi)]; } } while (0)
; __device__ __forceinline__ void partialSM(f32x16& p0, f32x16& p1, float& m_reg, float& mn, float& alpha) {
;   constexpr float C = SCALE * 1.4426950408889634f;
;   float pmax = p0[0]; for (int r = 1; r < 16; ++r) pmax = fmaxf(pmax, p0[r]); for (int r = 0; r < 16; ++r) pmax = fmaxf(pmax, p1[r]);
;   { auto rr = __builtin_amdgcn_permlane32_swap(__float_as_uint(pmax), __float_as_uint(pmax), false, false);
;     pmax = fmaxf(__uint_as_float(rr[0]), __uint_as_float(rr[1])); }
;   if (__builtin_expect(__all(pmax - m_reg <= THR / SCALE), 1)) { mn = m_reg; alpha = 1.f; }
;   else { mn = fmaxf(m_reg, pmax); alpha = __builtin_amdgcn_exp2f((m_reg - mn) * C); m_reg = mn; }
;   float mnC = -mn * C;
;   for (int r = 0; r < 16; ++r) p0[r] = fmaf(p0[r], C, mnC); for (int r = 0; r < 16; ++r) p1[r] = fmaf(p1[r], C, mnC);
;   for (int r = 0; r < 16; ++r) p0[r] = __builtin_amdgcn_exp2f(p0[r]);
; __device__ __forceinline__ void attn_unit(const bf16_t* __restrict__ Qb, const bf16_t* __restrict__ KV, const bf16_t* __restrict__ KP, bf16_t* __restrict__ Ob, ...
;     ...
;   f32x16 pA0, pA1, pB0, pB1; float mnA, mnB, alA, alB; bf16x8 pa0, pa1, pa2, pa3;
;   SLOAD(0); SWAIT(); SWRITE(0); __syncthreads();
;   qkt(pA0, pA1, KN_lds, KP_lds, qr, r32, hi); partialSM(pA0, pA1, m_reg, mnA, alA);
;   SLOAD(1);
;   SWAIT(); SWRITE(1); __syncthreads();
;   for (int j = 1; j + 1 < NT; j += 2) {
;     SBAR(); qkt(pB0, pB1, KN_lds + SHM_KN, KP_lds + SHM_KP, qr, r32, hi);
;     finishSM(pA0, pA1, alA, l_reg, pa0, pa1, pa2, pa3); SBAR();
;     SLOAD(j + 1); SBAR();
;     pv_d0(o, vb0, pa0, pa1, pa2, pa3); partialSM(pB0, pB1, m_reg, mnB, alB);
;     __syncthreads(); SWAIT(); SWRITE(0);
;     RESC(alB); __syncthreads();
	s_waitcnt vmcnt(0)
	ds_write_b128 v246, v[232:235]
	ds_write_b128 v247, v[236:239]
	ds_write_b128 v248, v[240:243]
	ds_write_b128 v244, v[224:227]
	ds_write_b128 v245, v[228:231]
	v_xor_b32_e32 v244, 0x4000, v244
	v_xor_b32_e32 v245, 0x4000, v245
	v_xor_b32_e32 v246, 0x4000, v246
	v_xor_b32_e32 v247, 0x4000, v247
	v_xor_b32_e32 v248, 0x2000, v248
	s_add_i32 s36, s35, 2
	s_min_u32 s36, s36, 67
	s_lshl_b32 s44, s36, 6
	s_add_i32 s45, s31, s44
	s_add_i32 s46, s24, s44
	s_add_i32 s46, s46, 0xffffff00
	s_cmp_lt_u32 s36, 4
	s_cselect_b32 s36, s45, s46
	s_add_i32 s37, s35, 1
	s_min_u32 s37, s37, 67
	s_lshl_b32 s44, s37, 6
	s_add_i32 s45, s31, s44
	s_add_i32 s46, s24, s44
	s_add_i32 s46, s46, 0xffffff00
	s_cmp_lt_u32 s37, 4
	s_cselect_b32 s37, s45, s46
	s_add_i32 s35, s35, 1
	s_lshl_b32 s44, s36, 12
	s_add_u32 s50, s47, s44
	s_addc_u32 s51, s63, 0
	s_add_u32 s52, s50, 0x20000
	s_addc_u32 s53, s51, 0
	s_lshl_b32 s44, s37, 12
	s_add_u32 s54, s47, s44
	s_addc_u32 s55, s63, 0
	s_add_u32 s56, s54, 0x20000
	s_addc_u32 s57, s55, 0
	s_lshl_b32 s44, s36, 10
	s_add_u32 s58, s60, s44
	s_addc_u32 s59, s61, 0
	global_load_dwordx4 v[232:235], v180, s[50:51]
	global_load_dwordx4 v[236:239], v180, s[52:53]
	global_load_dwordx4 v[224:227], v180, s[54:55] offset:256
	global_load_dwordx4 v[228:231], v180, s[56:57] offset:256
	global_load_dwordx4 v[240:243], v181, s[58:59]
	v_max3_f32 v250, v80, v81, v82
	v_max3_f32 v250, v250, v83, v84
	v_max3_f32 v250, v250, v85, v86
	v_max3_f32 v250, v250, v87, v88
	v_max3_f32 v250, v250, v89, v90
	v_max3_f32 v250, v250, v91, v92
	v_max3_f32 v250, v250, v93, v94
	v_max3_f32 v250, v250, v95, v64
	v_max3_f32 v250, v250, v65, v66
	v_max3_f32 v250, v250, v67, v68
	v_max3_f32 v250, v250, v69, v70
	v_max3_f32 v250, v250, v71, v72
	v_max3_f32 v250, v250, v73, v74
	v_max3_f32 v250, v250, v75, v76
	v_max3_f32 v250, v250, v77, v78
	v_max3_f32 v250, v250, v79, v79
	v_mov_b32_e32 v251, v250
	s_nop 1
	v_permlane32_swap_b32_e32 v250, v251
	v_max_f32_e32 v250, v250, v251
	v_sub_f32_e32 v251, v250, v175
	v_cmp_ge_f32_e32 vcc, s33, v251
	v_max_f32_e32 v249, v175, v250
	v_sub_f32_e32 v251, v175, v249
	v_mul_f32_e32 v251, 0x3dd53b94, v251
	v_exp_f32_e32 v251, v251
	s_nop 1
	s_cmp_eq_u64 vcc, exec
	s_cselect_b64 s[8:9], -1, 0
	v_cndmask_b32_e64 v177, v251, 1.0, s[8:9]
	v_cndmask_b32_e64 v175, v249, v175, s[8:9]
	v_cmp_gt_f32_e32 vcc, 1.0, v177
	s_nop 4
	s_cbranch_vccz .Lpp_nr_b
	s_and_saveexec_b64 s[42:43], s[6:7]
	ds_write_b32 v186, v177 offset:128
	s_or_b64 exec, exec, s[42:43]
	s_waitcnt lgkmcnt(0)
	v_add_u32_e32 v187, v179, v172
	ds_read_b128 v[192:195], v187 offset:128
	ds_read_b128 v[196:199], v187 offset:160
	ds_read_b128 v[200:203], v187 offset:192
	ds_read_b128 v[204:207], v187 offset:224
	s_waitcnt lgkmcnt(0)
	v_pk_mul_f32 v[0:1], v[0:1], v[192:193]
	v_pk_mul_f32 v[2:3], v[2:3], v[194:195]
	v_pk_mul_f32 v[4:5], v[4:5], v[196:197]
	v_pk_mul_f32 v[6:7], v[6:7], v[198:199]
	v_pk_mul_f32 v[8:9], v[8:9], v[200:201]
	v_pk_mul_f32 v[10:11], v[10:11], v[202:203]
	v_pk_mul_f32 v[12:13], v[12:13], v[204:205]
	v_pk_mul_f32 v[14:15], v[14:15], v[206:207]
	v_pk_mul_f32 v[48:49], v[48:49], v[192:193]
	v_pk_mul_f32 v[50:51], v[50:51], v[194:195]
	v_pk_mul_f32 v[52:53], v[52:53], v[196:197]
	v_pk_mul_f32 v[54:55], v[54:55], v[198:199]
	v_pk_mul_f32 v[56:57], v[56:57], v[200:201]
	v_pk_mul_f32 v[58:59], v[58:59], v[202:203]
	v_pk_mul_f32 v[60:61], v[60:61], v[204:205]
	v_pk_mul_f32 v[62:63], v[62:63], v[206:207]
	v_pk_mul_f32 v[32:33], v[32:33], v[192:193]
	v_pk_mul_f32 v[34:35], v[34:35], v[194:195]
	v_pk_mul_f32 v[36:37], v[36:37], v[196:197]
	v_pk_mul_f32 v[38:39], v[38:39], v[198:199]
	v_pk_mul_f32 v[40:41], v[40:41], v[200:201]
	v_pk_mul_f32 v[42:43], v[42:43], v[202:203]
	v_pk_mul_f32 v[44:45], v[44:45], v[204:205]
	v_pk_mul_f32 v[46:47], v[46:47], v[206:207]
	v_pk_mul_f32 v[16:17], v[16:17], v[192:193]
	v_pk_mul_f32 v[18:19], v[18:19], v[194:195]
	v_pk_mul_f32 v[20:21], v[20:21], v[196:197]
	v_pk_mul_f32 v[22:23], v[22:23], v[198:199]
	v_pk_mul_f32 v[24:25], v[24:25], v[200:201]
	v_pk_mul_f32 v[26:27], v[26:27], v[202:203]
	v_pk_mul_f32 v[28:29], v[28:29], v[204:205]
	v_pk_mul_f32 v[30:31], v[30:31], v[206:207]
.Lpp_nr_b:
	v_mul_f32_e32 v251, 0xbdd53b94, v175
	v_fmamk_f32 v80, v80, 0x3dd53b94, v251
	v_fmamk_f32 v81, v81, 0x3dd53b94, v251
	v_fmamk_f32 v82, v82, 0x3dd53b94, v251
	v_fmamk_f32 v83, v83, 0x3dd53b94, v251
	v_fmamk_f32 v84, v84, 0x3dd53b94, v251
	v_fmamk_f32 v85, v85, 0x3dd53b94, v251
	v_fmamk_f32 v86, v86, 0x3dd53b94, v251
	v_fmamk_f32 v87, v87, 0x3dd53b94, v251
	v_fmamk_f32 v88, v88, 0x3dd53b94, v251
	v_fmamk_f32 v89, v89, 0x3dd53b94, v251
	v_fmamk_f32 v90, v90, 0x3dd53b94, v251
	v_fmamk_f32 v91, v91, 0x3dd53b94, v251
	v_fmamk_f32 v92, v92, 0x3dd53b94, v251
	v_fmamk_f32 v93, v93, 0x3dd53b94, v251
	v_fmamk_f32 v94, v94, 0x3dd53b94, v251
	v_fmamk_f32 v95, v95, 0x3dd53b94, v251
	v_fmamk_f32 v64, v64, 0x3dd53b94, v251
	v_fmamk_f32 v65, v65, 0x3dd53b94, v251
	v_fmamk_f32 v66, v66, 0x3dd53b94, v251
	v_fmamk_f32 v67, v67, 0x3dd53b94, v251
	v_fmamk_f32 v68, v68, 0x3dd53b94, v251
	v_fmamk_f32 v69, v69, 0x3dd53b94, v251
	v_fmamk_f32 v70, v70, 0x3dd53b94, v251
	v_fmamk_f32 v71, v71, 0x3dd53b94, v251
	v_fmamk_f32 v72, v72, 0x3dd53b94, v251
	v_fmamk_f32 v73, v73, 0x3dd53b94, v251
	v_fmamk_f32 v74, v74, 0x3dd53b94, v251
	v_fmamk_f32 v75, v75, 0x3dd53b94, v251
	v_fmamk_f32 v76, v76, 0x3dd53b94, v251
	v_fmamk_f32 v77, v77, 0x3dd53b94, v251
	v_fmamk_f32 v78, v78, 0x3dd53b94, v251
	v_fmamk_f32 v79, v79, 0x3dd53b94, v251
	v_exp_f32_e32 v80, v80
	v_exp_f32_e32 v81, v81
	v_exp_f32_e32 v82, v82
	v_exp_f32_e32 v83, v83
	v_exp_f32_e32 v84, v84
; __device__ __forceinline__ void partialSM(f32x16& p0, f32x16& p1, float& m_reg, float& mn, float& alpha) {
;     ...
;   for (int r = 0; r < 16; ++r) p0[r] = __builtin_amdgcn_exp2f(p0[r]);
; }
; __device__ __forceinline__ void finishSM(f32x16& p0, f32x16& p1, float alpha, float& l_reg, bf16x8& pa0, bf16x8& pa1, bf16x8& pa2, bf16x8& pa3) {
;   for (int r = 0; r < 16; ++r) p1[r] = __builtin_amdgcn_exp2f(p1[r]);
;   float ps = 0; for (int r = 0; r < 16; ++r) ps += p0[r]; for (int r = 0; r < 16; ++r) ps += p1[r];
;   { auto rr = __builtin_amdgcn_permlane32_swap(__float_as_uint(ps), __float_as_uint(ps), false, false);
;     ps = __uint_as_float(rr[0]) + __uint_as_float(rr[1]); }
;   l_reg = l_reg * alpha + ps;
;     ...
;   PK4(p0, 0, pa0); PK4(p0, 8, pa1); PK4(p1, 0, pa2); PK4(p1, 8, pa3);
;     ...
; }
; __device__ __forceinline__ void qkt(f32x16& p0, f32x16& p1, const char* Kn, const char* Kp, const bf16x8* qr, int r32, int hi) {
;   p0 = f32x16{}; p1 = f32x16{};
; #pragma unroll
;   for (int d0 = 0; d0 < 8; ++d0) { int cb = (d0 * 16 + hi * 8) * 2;
;     bf16x8 b0 = *reinterpret_cast<const bf16x8*>(Kn + KSWZ(r32, cb));
;     bf16x8 b1 = *reinterpret_cast<const bf16x8*>(Kn + KSWZ(32 + r32, cb));
;     p0 = __builtin_amdgcn_mfma_f32_32x32x16_bf16(b0, qr[d0], p0, 0, 0, 0);
;     p1 = __builtin_amdgcn_mfma_f32_32x32x16_bf16(b1, qr[d0], p1, 0, 0, 0); }
; #pragma unroll
;   for (int d1 = 0; d1 < 4; ++d1) { int cb = (d1 * 16 + hi * 8) * 2;
;     bf16x8 b0 = *reinterpret_cast<const bf16x8*>(Kp + KPSWZ(r32, cb));
;     bf16x8 b1 = *reinterpret_cast<const bf16x8*>(Kp + KPSWZ(32 + r32, cb));
;     p0 = __builtin_amdgcn_mfma_f32_32x32x16_bf16(b0, qr[8 + d1], p0, 0, 0, 0);
;     p1 = __builtin_amdgcn_mfma_f32_32x32x16_bf16(b1, qr[8 + d1], p1, 0, 0, 0); }
; }
	v_exp_f32_e32 v85, v85
	v_exp_f32_e32 v86, v86
	v_exp_f32_e32 v87, v87
	v_exp_f32_e32 v88, v88
	v_exp_f32_e32 v89, v89
	v_exp_f32_e32 v90, v90
	v_exp_f32_e32 v91, v91
	v_exp_f32_e32 v92, v92
	v_exp_f32_e32 v93, v93
	v_exp_f32_e32 v94, v94
	v_exp_f32_e32 v95, v95
	v_exp_f32_e32 v64, v64
	v_exp_f32_e32 v65, v65
	v_exp_f32_e32 v66, v66
	v_exp_f32_e32 v67, v67
	v_exp_f32_e32 v68, v68
	v_exp_f32_e32 v69, v69
	v_exp_f32_e32 v70, v70
	v_exp_f32_e32 v71, v71
	v_exp_f32_e32 v72, v72
	v_exp_f32_e32 v73, v73
	v_exp_f32_e32 v74, v74
	v_exp_f32_e32 v75, v75
	v_exp_f32_e32 v76, v76
	v_exp_f32_e32 v77, v77
	v_exp_f32_e32 v78, v78
	v_exp_f32_e32 v79, v79
	s_nop 0
	v_add_f32_e32 v249, v80, v81
	v_add_f32_e32 v249, v82, v249
	v_add_f32_e32 v249, v83, v249
	v_add_f32_e32 v249, v84, v249
	v_add_f32_e32 v249, v85, v249
	v_add_f32_e32 v249, v86, v249
	v_add_f32_e32 v249, v87, v249
	v_add_f32_e32 v249, v88, v249
	v_add_f32_e32 v249, v89, v249
	v_add_f32_e32 v249, v90, v249
	v_add_f32_e32 v249, v91, v249
	v_add_f32_e32 v249, v92, v249
	v_add_f32_e32 v249, v93, v249
	v_add_f32_e32 v249, v94, v249
	v_add_f32_e32 v249, v95, v249
	v_add_f32_e32 v249, v64, v249
	v_add_f32_e32 v249, v65, v249
	v_add_f32_e32 v249, v66, v249
	v_add_f32_e32 v249, v67, v249
	v_add_f32_e32 v249, v68, v249
	v_add_f32_e32 v249, v69, v249
	v_add_f32_e32 v249, v70, v249
	v_add_f32_e32 v249, v71, v249
	v_add_f32_e32 v249, v72, v249
	v_add_f32_e32 v249, v73, v249
	v_add_f32_e32 v249, v74, v249
	v_add_f32_e32 v249, v75, v249
	v_add_f32_e32 v249, v76, v249
	v_add_f32_e32 v249, v77, v249
	v_add_f32_e32 v249, v78, v249
	v_add_f32_e32 v249, v79, v249
	v_mov_b32_e32 v250, v249
	s_nop 1
	v_permlane32_swap_b32_e32 v249, v250
	v_add_f32_e32 v249, v249, v250
	v_fma_f32 v176, v176, v177, v249
	v_cvt_pk_bf16_f32 v144, v80, v81
	v_cvt_pk_bf16_f32 v145, v82, v83
	v_cvt_pk_bf16_f32 v146, v84, v85
	v_cvt_pk_bf16_f32 v147, v86, v87
	v_cvt_pk_bf16_f32 v148, v88, v89
	v_cvt_pk_bf16_f32 v149, v90, v91
	v_cvt_pk_bf16_f32 v150, v92, v93
	v_cvt_pk_bf16_f32 v151, v94, v95
	v_cvt_pk_bf16_f32 v152, v64, v65
	v_cvt_pk_bf16_f32 v153, v66, v67
	v_cvt_pk_bf16_f32 v154, v68, v69
	v_cvt_pk_bf16_f32 v155, v70, v71
	v_cvt_pk_bf16_f32 v156, v72, v73
	v_cvt_pk_bf16_f32 v157, v74, v75
	v_cvt_pk_bf16_f32 v158, v76, v77
	v_cvt_pk_bf16_f32 v159, v78, v79
	s_nop 1
	v_permlane32_swap_b32_e32 v144, v146
	v_permlane32_swap_b32_e32 v145, v147
	v_permlane32_swap_b32_e32 v148, v150
	v_permlane32_swap_b32_e32 v149, v151
	v_permlane32_swap_b32_e32 v152, v154
	v_permlane32_swap_b32_e32 v153, v155
	v_permlane32_swap_b32_e32 v156, v158
	v_permlane32_swap_b32_e32 v157, v159
	s_waitcnt lgkmcnt(0)
	s_barrier
	s_add_i32 s11, s11, 1
	s_cmp_eq_u32 s11, 68
	s_cbranch_scc1 .Lpp_last
	ds_read_b128 v[192:195], v160
	ds_read_b128 v[196:199], v160 offset:8192
	ds_read_b128 v[200:203], v161
	ds_read_b128 v[204:207], v161 offset:8192
	ds_read_b128 v[208:211], v162
	ds_read_b128 v[212:215], v162 offset:8192
	ds_read_b64_tr_b16 v[216:217], v174 offset:16384
	ds_read_b64_tr_b16 v[218:219], v174 offset:18432
	ds_read_b64_tr_b16 v[220:221], v174 offset:20480
	ds_read_b64_tr_b16 v[222:223], v174 offset:22528
	s_waitcnt lgkmcnt(9)
	v_mfma_f32_32x32x16_bf16 v[80:95], v[192:195], v[136:139], 0
	ds_read_b128 v[192:195], v163
	s_waitcnt lgkmcnt(9)
	v_mfma_f32_32x32x16_bf16 v[64:79], v[196:199], v[136:139], 0
	ds_read_b128 v[196:199], v163 offset:8192
	s_waitcnt lgkmcnt(9)
	v_mfma_f32_32x32x16_bf16 v[80:95], v[200:203], v[132:135], v[80:95]
	ds_read_b128 v[200:203], v164
	s_waitcnt lgkmcnt(9)
	v_mfma_f32_32x32x16_bf16 v[64:79], v[204:207], v[132:135], v[64:79]
	ds_read_b128 v[204:207], v164 offset:8192
	s_waitcnt lgkmcnt(9)
	v_mfma_f32_32x32x16_bf16 v[80:95], v[208:211], v[128:131], v[80:95]
	ds_read_b128 v[208:211], v165
	s_waitcnt lgkmcnt(9)
	v_mfma_f32_32x32x16_bf16 v[64:79], v[212:215], v[128:131], v[64:79]
	ds_read_b128 v[212:215], v165 offset:8192
	s_waitcnt lgkmcnt(5)
	v_mfma_f32_32x32x16_bf16 v[80:95], v[192:195], v[124:127], v[80:95]
	ds_read_b128 v[192:195], v166
	s_waitcnt lgkmcnt(5)
	v_mfma_f32_32x32x16_bf16 v[64:79], v[196:199], v[124:127], v[64:79]
	ds_read_b128 v[196:199], v166 offset:8192
	s_waitcnt lgkmcnt(5)
	v_mfma_f32_32x32x16_bf16 v[80:95], v[200:203], v[120:123], v[80:95]
	ds_read_b128 v[200:203], v167
	s_waitcnt lgkmcnt(5)
	v_mfma_f32_32x32x16_bf16 v[64:79], v[204:207], v[120:123], v[64:79]
	ds_read_b128 v[204:207], v167 offset:8192
	s_waitcnt lgkmcnt(5)
	v_mfma_f32_32x32x16_bf16 v[80:95], v[208:211], v[140:143], v[80:95]
	ds_read_b128 v[208:211], v168
	s_waitcnt lgkmcnt(5)
	v_mfma_f32_32x32x16_bf16 v[64:79], v[212:215], v[140:143], v[64:79]
	ds_read_b128 v[212:215], v168 offset:4096
	s_waitcnt lgkmcnt(5)
	v_mfma_f32_32x32x16_bf16 v[80:95], v[192:195], v[116:119], v[80:95]
	ds_read_b128 v[192:195], v169
	s_waitcnt lgkmcnt(5)
	v_mfma_f32_32x32x16_bf16 v[64:79], v[196:199], v[116:119], v[64:79]
	ds_read_b128 v[196:199], v169 offset:4096
	s_waitcnt lgkmcnt(5)
	v_mfma_f32_32x32x16_bf16 v[80:95], v[200:203], v[112:115], v[80:95]
	ds_read_b128 v[200:203], v170
	s_waitcnt lgkmcnt(5)
	v_mfma_f32_32x32x16_bf16 v[64:79], v[204:207], v[112:115], v[64:79]
	ds_read_b128 v[204:207], v170 offset:4096
	s_waitcnt lgkmcnt(5)
	v_mfma_f32_32x32x16_bf16 v[80:95], v[208:211], v[108:111], v[80:95]
	ds_read_b128 v[208:211], v171
	s_waitcnt lgkmcnt(5)
	v_mfma_f32_32x32x16_bf16 v[64:79], v[212:215], v[108:111], v[64:79]
	ds_read_b128 v[212:215], v171 offset:4096
	s_waitcnt lgkmcnt(5)
	v_mfma_f32_32x32x16_bf16 v[80:95], v[192:195], v[104:107], v[80:95]
	ds_read_b64_tr_b16 v[192:193], v174 offset:24576
	ds_read_b64_tr_b16 v[194:195], v174 offset:26624
	s_waitcnt lgkmcnt(6)
; #define SBAR() __builtin_amdgcn_sched_barrier(0)
; __device__ __forceinline__ int v_st(int k, int c) { const int kk = (k & ~0xC) | ((k & 4) << 1) | ((k & 8) >> 1); return ((kk >> 3) * 4 + (c >> 5)) * 512 + ((kk & 7) * 32 + (c & 31)) * 2; }
; __device__ __forceinline__ int v_rd_base(int lane) { return ((lane & 3) << 3) | (((lane >> 2) & 3) << 6) | (((lane >> 4) & 1) << 5) | (((lane >> 5) & 1) << 8); }
; template <int OFF> __device__ __forceinline__ s16x4 tr_read(int vb) {
;   s16x4 r; asm volatile("ds_read_b64_tr_b16 %0, %1 offset:%2" : "=&v"(r) : "v"(vb), "i"(OFF) : "memory"); return r;
; }
; template <int D0> __device__ __forceinline__ void pv_one(f32x16& od, int vb, bf16x8 pa0, bf16x8 pa1, bf16x8 pa2, bf16x8 pa3) {
;   const s16x4 l0 = tr_read<v_rd_off(D0, 0, 0)>(vb), h0 = tr_read<v_rd_off(D0, 0, 1)>(vb), l1 = tr_read<v_rd_off(D0, 1, 0)>(vb), h1 = tr_read<v_rd_off(D0, 1, 1)>(vb);
;   const s16x4 l2 = tr_read<v_rd_off(D0, 2, 0)>(vb), h2 = tr_read<v_rd_off(D0, 2, 1)>(vb), l3 = tr_read<v_rd_off(D0, 3, 0)>(vb), h3 = tr_read<v_rd_off(D0, 3, 1)>(vb);
;   asm volatile("s_waitcnt lgkmcnt(0)" ::: "memory"); SBAR();
;     ...
;   od = __builtin_amdgcn_mfma_f32_32x32x16_bf16(pa0, PK(l0, h0), od, 0, 0, 0);
;   od = __builtin_amdgcn_mfma_f32_32x32x16_bf16(pa1, PK(l1, h1), od, 0, 0, 0);
;   od = __builtin_amdgcn_mfma_f32_32x32x16_bf16(pa2, PK(l2, h2), od, 0, 0, 0);
;   od = __builtin_amdgcn_mfma_f32_32x32x16_bf16(pa3, PK(l3, h3), od, 0, 0, 0);
;     ...
; }
; __device__ __forceinline__ void pv_d0(f32x16* o, int vb, bf16x8 pa0, bf16x8 pa1, bf16x8 pa2, bf16x8 pa3) {
;   pv_one<0>(o[0], vb, pa0, pa1, pa2, pa3); pv_one<1>(o[1], vb, pa0, pa1, pa2, pa3); pv_one<2>(o[2], vb, pa0, pa1, pa2, pa3); pv_one<3>(o[3], vb, pa0, pa1, pa2, pa3);
; __device__ __forceinline__ void attn_unit(const bf16_t* __restrict__ Qb, const bf16_t* __restrict__ KV, const bf16_t* __restrict__ KP, bf16_t* __restrict__ Ob, ...
;     ...
;   SBAR(); qkt(pB0, pB1, KN_lds + SHM_KN, KP_lds + SHM_KP, qr, r32, hi);
;   finishSM(pA0, pA1, alA, l_reg, pa0, pa1, pa2, pa3); SBAR();
;   pv_d0(o, vb0, pa0, pa1, pa2, pa3); partialSM(pB0, pB1, m_reg, mnB, alB);
;   __syncthreads(); RESC(alB);
;   finishSM(pB0, pB1, alB, l_reg, pa0, pa1, pa2, pa3); SBAR();
;   pv_d0(o, vb0 + SHM_V, pa0, pa1, pa2, pa3);
;   if (hi == 0) li_l[r32] = l_reg; asm volatile("s_waitcnt lgkmcnt(0)" ::: "memory");
	v_mfma_f32_32x32x16_bf16 v[64:79], v[196:199], v[104:107], v[64:79]
	ds_read_b64_tr_b16 v[196:197], v174 offset:28672
	ds_read_b64_tr_b16 v[198:199], v174 offset:30720
	s_waitcnt lgkmcnt(7)
	v_mfma_f32_32x32x16_bf16 v[80:95], v[200:203], v[100:103], v[80:95]
	ds_read_b64_tr_b16 v[200:201], v174 offset:16896
	ds_read_b64_tr_b16 v[202:203], v174 offset:18944
	s_waitcnt lgkmcnt(8)
	v_mfma_f32_32x32x16_bf16 v[64:79], v[204:207], v[100:103], v[64:79]
	ds_read_b64_tr_b16 v[204:205], v174 offset:20992
	ds_read_b64_tr_b16 v[206:207], v174 offset:23040
	s_waitcnt lgkmcnt(9)
	v_mfma_f32_32x32x16_bf16 v[80:95], v[208:211], v[96:99], v[80:95]
	ds_read_b64_tr_b16 v[208:209], v174 offset:25088
	ds_read_b64_tr_b16 v[210:211], v174 offset:27136
	s_waitcnt lgkmcnt(10)
	v_mfma_f32_32x32x16_bf16 v[64:79], v[212:215], v[96:99], v[64:79]
	ds_read_b64_tr_b16 v[212:213], v174 offset:29184
	ds_read_b64_tr_b16 v[214:215], v174 offset:31232
	s_waitcnt lgkmcnt(15)
	v_mfma_f32_32x32x16_bf16 v[0:15], v[144:147], v[216:219], v[0:15]
	ds_read_b64_tr_b16 v[216:217], v174 offset:17408
	ds_read_b64_tr_b16 v[218:219], v174 offset:19456
	s_waitcnt lgkmcnt(15)
	v_mfma_f32_32x32x16_bf16 v[0:15], v[148:151], v[220:223], v[0:15]
	ds_read_b64_tr_b16 v[220:221], v174 offset:21504
	ds_read_b64_tr_b16 v[222:223], v174 offset:23552
	s_waitcnt lgkmcnt(14)
	v_mfma_f32_32x32x16_bf16 v[0:15], v[152:155], v[192:195], v[0:15]
	ds_read_b64_tr_b16 v[192:193], v174 offset:25600
	ds_read_b64_tr_b16 v[194:195], v174 offset:27648
	s_waitcnt lgkmcnt(14)
	v_mfma_f32_32x32x16_bf16 v[0:15], v[156:159], v[196:199], v[0:15]
	ds_read_b64_tr_b16 v[196:197], v174 offset:29696
	ds_read_b64_tr_b16 v[198:199], v174 offset:31744
	s_waitcnt lgkmcnt(14)
	v_mfma_f32_32x32x16_bf16 v[48:63], v[144:147], v[200:203], v[48:63]
	ds_read_b64_tr_b16 v[200:201], v174 offset:17920
	ds_read_b64_tr_b16 v[202:203], v174 offset:19968
	s_waitcnt lgkmcnt(14)
	v_mfma_f32_32x32x16_bf16 v[48:63], v[148:151], v[204:207], v[48:63]
	ds_read_b64_tr_b16 v[204:205], v174 offset:22016
	ds_read_b64_tr_b16 v[206:207], v174 offset:24064
	s_waitcnt lgkmcnt(14)
	v_mfma_f32_32x32x16_bf16 v[48:63], v[152:155], v[208:211], v[48:63]
	ds_read_b64_tr_b16 v[208:209], v174 offset:26112
	ds_read_b64_tr_b16 v[210:211], v174 offset:28160
	s_waitcnt lgkmcnt(14)
	v_mfma_f32_32x32x16_bf16 v[48:63], v[156:159], v[212:215], v[48:63]
	ds_read_b64_tr_b16 v[212:213], v174 offset:30208
	ds_read_b64_tr_b16 v[214:215], v174 offset:32256
	s_waitcnt lgkmcnt(14)
	v_mfma_f32_32x32x16_bf16 v[32:47], v[144:147], v[216:219], v[32:47]
	s_waitcnt lgkmcnt(12)
	v_mfma_f32_32x32x16_bf16 v[32:47], v[148:151], v[220:223], v[32:47]
	s_waitcnt lgkmcnt(10)
	v_mfma_f32_32x32x16_bf16 v[32:47], v[152:155], v[192:195], v[32:47]
	s_waitcnt lgkmcnt(8)
	v_mfma_f32_32x32x16_bf16 v[32:47], v[156:159], v[196:199], v[32:47]
	s_waitcnt lgkmcnt(6)
	v_mfma_f32_32x32x16_bf16 v[16:31], v[144:147], v[200:203], v[16:31]
	s_waitcnt lgkmcnt(4)
	v_mfma_f32_32x32x16_bf16 v[16:31], v[148:151], v[204:207], v[16:31]
	s_waitcnt lgkmcnt(2)
	v_mfma_f32_32x32x16_bf16 v[16:31], v[152:155], v[208:211], v[16:31]
	s_waitcnt lgkmcnt(0)
	v_mfma_f32_32x32x16_bf16 v[16:31], v[156:159], v[212:215], v[16:31]
	s_barrier
	s_branch .Lpp_loop
.Lpp_last:
	ds_read_b64_tr_b16 v[216:217], v174 offset:16384
	ds_read_b64_tr_b16 v[218:219], v174 offset:18432
	ds_read_b64_tr_b16 v[220:221], v174 offset:20480
	ds_read_b64_tr_b16 v[222:223], v174 offset:22528
	ds_read_b64_tr_b16 v[192:193], v174 offset:24576
	ds_read_b64_tr_b16 v[194:195], v174 offset:26624
	ds_read_b64_tr_b16 v[196:197], v174 offset:28672
	ds_read_b64_tr_b16 v[198:199], v174 offset:30720
	ds_read_b64_tr_b16 v[200:201], v174 offset:16896
	ds_read_b64_tr_b16 v[202:203], v174 offset:18944
	ds_read_b64_tr_b16 v[204:205], v174 offset:20992
	ds_read_b64_tr_b16 v[206:207], v174 offset:23040
	ds_read_b64_tr_b16 v[208:209], v174 offset:25088
	ds_read_b64_tr_b16 v[210:211], v174 offset:27136
	ds_read_b64_tr_b16 v[212:213], v174 offset:29184
	ds_read_b64_tr_b16 v[214:215], v174 offset:31232
	s_waitcnt lgkmcnt(14)
	s_nop 0
	v_mfma_f32_32x32x16_bf16 v[0:15], v[144:147], v[216:219], v[0:15]
	ds_read_b64_tr_b16 v[216:217], v174 offset:17408
	ds_read_b64_tr_b16 v[218:219], v174 offset:19456
	s_waitcnt lgkmcnt(14)
	v_mfma_f32_32x32x16_bf16 v[0:15], v[148:151], v[220:223], v[0:15]
	ds_read_b64_tr_b16 v[220:221], v174 offset:21504
	ds_read_b64_tr_b16 v[222:223], v174 offset:23552
	s_waitcnt lgkmcnt(14)
	v_mfma_f32_32x32x16_bf16 v[0:15], v[152:155], v[192:195], v[0:15]
	ds_read_b64_tr_b16 v[192:193], v174 offset:25600
	ds_read_b64_tr_b16 v[194:195], v174 offset:27648
	s_waitcnt lgkmcnt(14)
	v_mfma_f32_32x32x16_bf16 v[0:15], v[156:159], v[196:199], v[0:15]
	ds_read_b64_tr_b16 v[196:197], v174 offset:29696
	ds_read_b64_tr_b16 v[198:199], v174 offset:31744
	s_waitcnt lgkmcnt(14)
	v_mfma_f32_32x32x16_bf16 v[48:63], v[144:147], v[200:203], v[48:63]
	ds_read_b64_tr_b16 v[200:201], v174 offset:17920
	ds_read_b64_tr_b16 v[202:203], v174 offset:19968
	s_waitcnt lgkmcnt(14)
	v_mfma_f32_32x32x16_bf16 v[48:63], v[148:151], v[204:207], v[48:63]
	ds_read_b64_tr_b16 v[204:205], v174 offset:22016
	ds_read_b64_tr_b16 v[206:207], v174 offset:24064
	s_waitcnt lgkmcnt(14)
	v_mfma_f32_32x32x16_bf16 v[48:63], v[152:155], v[208:211], v[48:63]
	ds_read_b64_tr_b16 v[208:209], v174 offset:26112
	ds_read_b64_tr_b16 v[210:211], v174 offset:28160
	s_waitcnt lgkmcnt(14)
	v_mfma_f32_32x32x16_bf16 v[48:63], v[156:159], v[212:215], v[48:63]
	ds_read_b64_tr_b16 v[212:213], v174 offset:30208
	ds_read_b64_tr_b16 v[214:215], v174 offset:32256
	s_waitcnt lgkmcnt(14)
	v_mfma_f32_32x32x16_bf16 v[32:47], v[144:147], v[216:219], v[32:47]
	s_waitcnt lgkmcnt(12)
	v_mfma_f32_32x32x16_bf16 v[32:47], v[148:151], v[220:223], v[32:47]
	s_waitcnt lgkmcnt(10)
	v_mfma_f32_32x32x16_bf16 v[32:47], v[152:155], v[192:195], v[32:47]
	s_waitcnt lgkmcnt(8)
	v_mfma_f32_32x32x16_bf16 v[32:47], v[156:159], v[196:199], v[32:47]
	s_waitcnt lgkmcnt(6)
	v_mfma_f32_32x32x16_bf16 v[16:31], v[144:147], v[200:203], v[16:31]
	s_waitcnt lgkmcnt(4)
	v_mfma_f32_32x32x16_bf16 v[16:31], v[148:151], v[204:207], v[16:31]
	s_waitcnt lgkmcnt(2)
	v_mfma_f32_32x32x16_bf16 v[16:31], v[152:155], v[208:211], v[16:31]
	s_waitcnt lgkmcnt(0)
	v_mfma_f32_32x32x16_bf16 v[16:31], v[156:159], v[212:215], v[16:31]
	s_barrier
	s_cmp_lg_u32 s41, 0
	s_cbranch_scc1 .Lpp_fin
	s_barrier
.Lpp_fin:
	s_waitcnt vmcnt(0)
	s_and_saveexec_b64 s[8:9], s[6:7]
	ds_write_b32 v186, v176
	s_branch .LBB0_1451
